# residual epilogues (out-proj, MLP-out): counted waits re-derived with the interleaved stores included (vmcnt 8->12/16, 4->12, 0->8) so a stage no longer waits for the previous stage's store acks
# speedup vs baseline: 1.0161x; 1.0013x over previous
.LBB0_781:
	s_or_b64 exec, exec, s[22:23]
	v_or_b32_e32 v188, 48, v184
	v_ashrrev_i32_e32 v189, 31, v188
	s_waitcnt lgkmcnt(0)
	v_lshlrev_b64 v[112:113], 10, v[188:189]
	v_lshl_add_u64 v[112:113], v[112:113], 0, v[182:183]
	v_readlane_b32 s22, v247, 5
	v_lshlrev_b64 v[112:113], 1, v[112:113]
	v_readlane_b32 s23, v247, 6
	s_nop 1
	v_lshl_add_u64 v[194:195], s[22:23], 0, v[112:113]
	v_readlane_b32 s22, v249, 0
	v_readlane_b32 s23, v249, 1
	global_load_dwordx4 v[120:123], v[194:195], off offset:0
	s_nop 1
	v_lshl_add_u64 v[196:197], s[22:23], 0, v[112:113]
	global_load_dwordx4 v[124:127], v[196:197], off offset:0
	global_load_dwordx4 v[116:119], v[194:195], off offset:256
	global_load_dwordx4 v[112:115], v[196:197], off offset:256
	s_waitcnt vmcnt(12)
	s_nop 0
	v_lshlrev_b32_e32 v185, 16, v153
	v_lshlrev_b32_e32 v209, 16, v152
	v_and_b32_e32 v153, 0xffff0000, v153
	v_and_b32_e32 v152, 0xffff0000, v152
	v_or_b32_sdwa v211, v157, v185 dst_sel:DWORD dst_unused:UNUSED_PAD src0_sel:WORD_0 src1_sel:DWORD
	v_or_b32_sdwa v153, v157, v153 dst_sel:DWORD dst_unused:UNUSED_PAD src0_sel:WORD_1 src1_sel:DWORD
	v_or_b32_sdwa v152, v156, v152 dst_sel:DWORD dst_unused:UNUSED_PAD src0_sel:WORD_1 src1_sel:DWORD
	v_mov_b32_e32 v157, v110
	v_mov_b32_e32 v110, v109
	v_or_b32_sdwa v210, v156, v209 dst_sel:DWORD dst_unused:UNUSED_PAD src0_sel:WORD_0 src1_sel:DWORD
	v_mov_b32_e32 v156, v108
	v_pk_add_f32 v[152:153], v[110:111], v[152:153]
	v_pk_add_f32 v[156:157], v[156:157], v[210:211]
	v_and_b32_e32 v109, 0xffff0000, v152
	v_and_b32_e32 v108, 0xffff0000, v156
	v_mul_f32_e32 v185, v109, v109
	v_fmac_f32_e32 v185, v108, v108
	v_and_b32_e32 v108, 0xffff0000, v157
	v_fmac_f32_e32 v185, v108, v108
	v_and_b32_e32 v110, 0xffff0000, v153
	v_fmac_f32_e32 v185, v110, v110
	v_or_b32_sdwa v108, v156, v109 dst_sel:DWORD dst_unused:UNUSED_PAD src0_sel:WORD_1 src1_sel:DWORD
	v_or_b32_sdwa v109, v157, v110 dst_sel:DWORD dst_unused:UNUSED_PAD src0_sel:WORD_1 src1_sel:DWORD
	v_lshlrev_b32_e32 v110, 16, v155
	v_lshlrev_b32_e32 v209, 16, v154
	v_and_b32_e32 v155, 0xffff0000, v155
	v_and_b32_e32 v154, 0xffff0000, v154
	v_or_b32_sdwa v111, v159, v110 dst_sel:DWORD dst_unused:UNUSED_PAD src0_sel:WORD_0 src1_sel:DWORD
	v_or_b32_sdwa v110, v158, v209 dst_sel:DWORD dst_unused:UNUSED_PAD src0_sel:WORD_0 src1_sel:DWORD
	v_or_b32_sdwa v155, v159, v155 dst_sel:DWORD dst_unused:UNUSED_PAD src0_sel:WORD_1 src1_sel:DWORD
	v_or_b32_sdwa v154, v158, v154 dst_sel:DWORD dst_unused:UNUSED_PAD src0_sel:WORD_1 src1_sel:DWORD
	v_mov_b32_e32 v158, v104
	v_mov_b32_e32 v159, v106
	v_mov_b32_e32 v106, v105
	v_pk_add_f32 v[158:159], v[158:159], v[110:111]
	v_pk_add_f32 v[104:105], v[106:107], v[154:155]
	v_and_b32_e32 v106, 0xffff0000, v158
	v_and_b32_e32 v107, 0xffff0000, v104
	v_and_b32_e32 v155, 0xffff0000, v105
	v_lshlrev_b32_e32 v152, 16, v152
	v_lshlrev_b32_e32 v104, 16, v104
	v_or_b32_sdwa v110, v158, v107 dst_sel:DWORD dst_unused:UNUSED_PAD src0_sel:WORD_1 src1_sel:DWORD
	v_or_b32_sdwa v111, v159, v155 dst_sel:DWORD dst_unused:UNUSED_PAD src0_sel:WORD_1 src1_sel:DWORD
	v_fmac_f32_e32 v185, v106, v106
	v_lshlrev_b32_e32 v153, 16, v153
	v_lshlrev_b32_e32 v105, 16, v105
	v_and_or_b32 v106, v158, s4, v104
	v_and_or_b32 v104, v156, s4, v152
	v_fmac_f32_e32 v185, v107, v107
	v_and_or_b32 v107, v159, s4, v105
	v_and_or_b32 v105, v157, s4, v153
	global_store_dwordx4 v[200:201], v[108:111], off
	global_store_dwordx4 v[202:203], v[104:107], off
	v_and_b32_e32 v154, 0xffff0000, v159
	v_and_b32_e32 v108, 0xffff0000, v148
	v_lshlrev_b32_e32 v104, 16, v149
	v_lshlrev_b32_e32 v106, 16, v148
	v_or_b32_sdwa v105, v145, v104 dst_sel:DWORD dst_unused:UNUSED_PAD src0_sel:WORD_0 src1_sel:DWORD
	v_or_b32_sdwa v104, v144, v106 dst_sel:DWORD dst_unused:UNUSED_PAD src0_sel:WORD_0 src1_sel:DWORD
	v_and_b32_e32 v106, 0xffff0000, v149
	v_or_b32_sdwa v107, v145, v106 dst_sel:DWORD dst_unused:UNUSED_PAD src0_sel:WORD_1 src1_sel:DWORD
	v_or_b32_sdwa v106, v144, v108 dst_sel:DWORD dst_unused:UNUSED_PAD src0_sel:WORD_1 src1_sel:DWORD
	v_mov_b32_e32 v108, v100
	v_mov_b32_e32 v109, v102
	v_fmac_f32_e32 v185, v154, v154
	v_pk_add_f32 v[104:105], v[108:109], v[104:105]
	v_mov_b32_e32 v102, v101
	v_fmac_f32_e32 v185, v155, v155
	v_pk_add_f32 v[106:107], v[102:103], v[106:107]
	v_and_b32_e32 v100, 0xffff0000, v104
	v_lshlrev_b32_e32 v102, 16, v151
	v_lshlrev_b32_e32 v108, 16, v150
	v_fmac_f32_e32 v185, v100, v100
	v_and_b32_e32 v100, 0xffff0000, v106
	v_or_b32_sdwa v103, v147, v102 dst_sel:DWORD dst_unused:UNUSED_PAD src0_sel:WORD_0 src1_sel:DWORD
	v_or_b32_sdwa v102, v146, v108 dst_sel:DWORD dst_unused:UNUSED_PAD src0_sel:WORD_0 src1_sel:DWORD
	v_and_b32_e32 v108, 0xffff0000, v151
	v_and_b32_e32 v110, 0xffff0000, v150
	v_fmac_f32_e32 v185, v100, v100
	v_and_b32_e32 v101, 0xffff0000, v105
	v_or_b32_sdwa v109, v147, v108 dst_sel:DWORD dst_unused:UNUSED_PAD src0_sel:WORD_1 src1_sel:DWORD
	v_or_b32_sdwa v108, v146, v110 dst_sel:DWORD dst_unused:UNUSED_PAD src0_sel:WORD_1 src1_sel:DWORD
	v_mov_b32_e32 v110, v96
	v_mov_b32_e32 v111, v98
	v_fmac_f32_e32 v185, v101, v101
	v_and_b32_e32 v101, 0xffff0000, v107
	v_pk_add_f32 v[110:111], v[110:111], v[102:103]
	v_mov_b32_e32 v98, v97
	v_fmac_f32_e32 v185, v101, v101
	v_pk_add_f32 v[96:97], v[98:99], v[108:109]
	v_and_b32_e32 v98, 0xffff0000, v110
	v_and_b32_e32 v99, 0xffff0000, v96
	v_fmac_f32_e32 v185, v98, v98
	v_and_b32_e32 v108, 0xffff0000, v111
	v_fmac_f32_e32 v185, v99, v99
	v_and_b32_e32 v109, 0xffff0000, v97
	v_fmac_f32_e32 v185, v108, v108
	v_fmac_f32_e32 v185, v109, v109
	ds_bpermute_b32 v108, v207, v185
	v_lshlrev_b32_e32 v96, 16, v96
	v_lshlrev_b32_e32 v98, 16, v106
	v_lshlrev_b32_e32 v97, 16, v97
	v_and_or_b32 v106, v110, s4, v96
	s_waitcnt lgkmcnt(0)
	v_add_f32_e32 v96, v185, v108
	v_or_b32_sdwa v102, v110, v99 dst_sel:DWORD dst_unused:UNUSED_PAD src0_sel:WORD_1 src1_sel:DWORD
	v_lshlrev_b32_e32 v99, 16, v107
	v_and_or_b32 v107, v111, s4, v97
	ds_bpermute_b32 v97, v208, v96
	v_or_b32_sdwa v100, v104, v100 dst_sel:DWORD dst_unused:UNUSED_PAD src0_sel:WORD_1 src1_sel:DWORD
	v_or_b32_sdwa v101, v105, v101 dst_sel:DWORD dst_unused:UNUSED_PAD src0_sel:WORD_1 src1_sel:DWORD
	v_or_b32_sdwa v103, v111, v109 dst_sel:DWORD dst_unused:UNUSED_PAD src0_sel:WORD_1 src1_sel:DWORD
	v_and_or_b32 v105, v105, s4, v99
	v_and_or_b32 v104, v104, s4, v98
	global_store_dwordx4 v[200:201], v[100:103], off offset:256
	global_store_dwordx4 v[202:203], v[104:107], off offset:256
	s_and_saveexec_b64 s[22:23], s[6:7]
	s_cbranch_execz .LBB0_783
	v_lshlrev_b64 v[98:99], 6, v[198:199]
	s_lshl_b32 s26, s50, 2
	v_lshl_add_u64 v[98:99], s[2:3], 0, v[98:99]
	s_ashr_i32 s27, s26, 31
	v_lshl_add_u64 v[98:99], s[26:27], 2, v[98:99]
	s_lshl_b32 s24, s46, 2
	v_lshl_add_u64 v[98:99], v[98:99], 0, s[24:25]
	s_waitcnt lgkmcnt(0)
	v_add_f32_e32 v96, v96, v97
	global_store_dword v[98:99], v96, off
.LBB0_783:
	s_or_b64 exec, exec, s[22:23]
	v_add_u32_e32 v144, 0x80, v184
	v_ashrrev_i32_e32 v145, 31, v144
	s_waitcnt lgkmcnt(0)
	v_lshlrev_b64 v[96:97], 10, v[144:145]
	v_lshl_add_u64 v[96:97], v[96:97], 0, v[182:183]
	v_readlane_b32 s22, v247, 5
	v_lshlrev_b64 v[96:97], 1, v[96:97]
	v_readlane_b32 s23, v247, 6
	s_nop 1
	v_lshl_add_u64 v[146:147], s[22:23], 0, v[96:97]
	v_readlane_b32 s22, v249, 0
	v_readlane_b32 s23, v249, 1
	global_load_dwordx4 v[104:107], v[146:147], off offset:0
	s_nop 1
	v_lshl_add_u64 v[148:149], s[22:23], 0, v[96:97]
	global_load_dwordx4 v[108:111], v[148:149], off offset:0
	global_load_dwordx4 v[100:103], v[146:147], off offset:256
	global_load_dwordx4 v[96:99], v[148:149], off offset:256
	s_waitcnt vmcnt(16)
	s_nop 0
	v_lshlrev_b32_e32 v150, 16, v137
	v_lshlrev_b32_e32 v152, 16, v136
	v_and_b32_e32 v137, 0xffff0000, v137
	v_and_b32_e32 v136, 0xffff0000, v136
	v_or_b32_sdwa v151, v141, v150 dst_sel:DWORD dst_unused:UNUSED_PAD src0_sel:WORD_0 src1_sel:DWORD
	v_or_b32_sdwa v137, v141, v137 dst_sel:DWORD dst_unused:UNUSED_PAD src0_sel:WORD_1 src1_sel:DWORD
	v_or_b32_sdwa v136, v140, v136 dst_sel:DWORD dst_unused:UNUSED_PAD src0_sel:WORD_1 src1_sel:DWORD
	v_mov_b32_e32 v141, v94
	v_mov_b32_e32 v94, v93
	v_or_b32_sdwa v150, v140, v152 dst_sel:DWORD dst_unused:UNUSED_PAD src0_sel:WORD_0 src1_sel:DWORD
	v_mov_b32_e32 v140, v92
	v_pk_add_f32 v[136:137], v[94:95], v[136:137]
	v_pk_add_f32 v[140:141], v[140:141], v[150:151]
	v_and_b32_e32 v93, 0xffff0000, v136
	v_and_b32_e32 v92, 0xffff0000, v140
	v_mul_f32_e32 v150, v93, v93
	v_fmac_f32_e32 v150, v92, v92
	v_and_b32_e32 v92, 0xffff0000, v141
	v_fmac_f32_e32 v150, v92, v92
	v_and_b32_e32 v94, 0xffff0000, v137
	v_fmac_f32_e32 v150, v94, v94
	v_or_b32_sdwa v92, v140, v93 dst_sel:DWORD dst_unused:UNUSED_PAD src0_sel:WORD_1 src1_sel:DWORD
	v_or_b32_sdwa v93, v141, v94 dst_sel:DWORD dst_unused:UNUSED_PAD src0_sel:WORD_1 src1_sel:DWORD
	v_lshlrev_b32_e32 v94, 16, v139
	v_lshlrev_b32_e32 v151, 16, v138
	v_and_b32_e32 v139, 0xffff0000, v139
	v_and_b32_e32 v138, 0xffff0000, v138
	v_or_b32_sdwa v95, v143, v94 dst_sel:DWORD dst_unused:UNUSED_PAD src0_sel:WORD_0 src1_sel:DWORD
	v_or_b32_sdwa v94, v142, v151 dst_sel:DWORD dst_unused:UNUSED_PAD src0_sel:WORD_0 src1_sel:DWORD
	v_or_b32_sdwa v139, v143, v139 dst_sel:DWORD dst_unused:UNUSED_PAD src0_sel:WORD_1 src1_sel:DWORD
	v_or_b32_sdwa v138, v142, v138 dst_sel:DWORD dst_unused:UNUSED_PAD src0_sel:WORD_1 src1_sel:DWORD
	v_mov_b32_e32 v142, v88
	v_mov_b32_e32 v143, v90
	v_mov_b32_e32 v90, v89
	v_pk_add_f32 v[142:143], v[142:143], v[94:95]
	v_pk_add_f32 v[88:89], v[90:91], v[138:139]
	v_and_b32_e32 v90, 0xffff0000, v142
	v_and_b32_e32 v91, 0xffff0000, v88
	v_and_b32_e32 v139, 0xffff0000, v89
	v_lshlrev_b32_e32 v136, 16, v136
	v_lshlrev_b32_e32 v88, 16, v88
	v_or_b32_sdwa v94, v142, v91 dst_sel:DWORD dst_unused:UNUSED_PAD src0_sel:WORD_1 src1_sel:DWORD
	v_or_b32_sdwa v95, v143, v139 dst_sel:DWORD dst_unused:UNUSED_PAD src0_sel:WORD_1 src1_sel:DWORD
	v_fmac_f32_e32 v150, v90, v90
	v_lshlrev_b32_e32 v137, 16, v137
	v_lshlrev_b32_e32 v89, 16, v89
	v_and_or_b32 v90, v142, s4, v88
	v_and_or_b32 v88, v140, s4, v136
	v_fmac_f32_e32 v150, v91, v91
	v_and_or_b32 v91, v143, s4, v89
	v_and_or_b32 v89, v141, s4, v137
	global_store_dwordx4 v[190:191], v[92:95], off
	global_store_dwordx4 v[192:193], v[88:91], off
	v_and_b32_e32 v138, 0xffff0000, v143
	v_and_b32_e32 v92, 0xffff0000, v132
	v_lshlrev_b32_e32 v88, 16, v133
	v_lshlrev_b32_e32 v90, 16, v132
	v_or_b32_sdwa v89, v129, v88 dst_sel:DWORD dst_unused:UNUSED_PAD src0_sel:WORD_0 src1_sel:DWORD
	v_or_b32_sdwa v88, v128, v90 dst_sel:DWORD dst_unused:UNUSED_PAD src0_sel:WORD_0 src1_sel:DWORD
	v_and_b32_e32 v90, 0xffff0000, v133
	v_or_b32_sdwa v91, v129, v90 dst_sel:DWORD dst_unused:UNUSED_PAD src0_sel:WORD_1 src1_sel:DWORD
	v_or_b32_sdwa v90, v128, v92 dst_sel:DWORD dst_unused:UNUSED_PAD src0_sel:WORD_1 src1_sel:DWORD
	v_mov_b32_e32 v92, v84
	v_mov_b32_e32 v93, v86
	v_fmac_f32_e32 v150, v138, v138
	v_pk_add_f32 v[88:89], v[92:93], v[88:89]
	v_mov_b32_e32 v86, v85
	v_fmac_f32_e32 v150, v139, v139
	v_pk_add_f32 v[90:91], v[86:87], v[90:91]
	v_and_b32_e32 v84, 0xffff0000, v88
	v_lshlrev_b32_e32 v86, 16, v135
	v_lshlrev_b32_e32 v92, 16, v134
	v_fmac_f32_e32 v150, v84, v84
	v_and_b32_e32 v84, 0xffff0000, v90
	v_or_b32_sdwa v87, v131, v86 dst_sel:DWORD dst_unused:UNUSED_PAD src0_sel:WORD_0 src1_sel:DWORD
	v_or_b32_sdwa v86, v130, v92 dst_sel:DWORD dst_unused:UNUSED_PAD src0_sel:WORD_0 src1_sel:DWORD
	v_and_b32_e32 v92, 0xffff0000, v135
	v_and_b32_e32 v94, 0xffff0000, v134
	v_fmac_f32_e32 v150, v84, v84
	v_and_b32_e32 v85, 0xffff0000, v89
	v_or_b32_sdwa v93, v131, v92 dst_sel:DWORD dst_unused:UNUSED_PAD src0_sel:WORD_1 src1_sel:DWORD
	v_or_b32_sdwa v92, v130, v94 dst_sel:DWORD dst_unused:UNUSED_PAD src0_sel:WORD_1 src1_sel:DWORD
	v_mov_b32_e32 v94, v80
	v_mov_b32_e32 v95, v82
	v_fmac_f32_e32 v150, v85, v85
	v_and_b32_e32 v85, 0xffff0000, v91
	v_pk_add_f32 v[94:95], v[94:95], v[86:87]
	v_mov_b32_e32 v82, v81
	v_fmac_f32_e32 v150, v85, v85
	v_pk_add_f32 v[80:81], v[82:83], v[92:93]
	v_and_b32_e32 v82, 0xffff0000, v94
	v_and_b32_e32 v83, 0xffff0000, v80
	v_fmac_f32_e32 v150, v82, v82
	v_and_b32_e32 v92, 0xffff0000, v95
	v_fmac_f32_e32 v150, v83, v83
	v_and_b32_e32 v93, 0xffff0000, v81
	v_fmac_f32_e32 v150, v92, v92
	v_fmac_f32_e32 v150, v93, v93
	ds_bpermute_b32 v92, v207, v150
	v_lshlrev_b32_e32 v80, 16, v80
	v_lshlrev_b32_e32 v82, 16, v90
	v_lshlrev_b32_e32 v81, 16, v81
	v_and_or_b32 v90, v94, s4, v80
	s_waitcnt lgkmcnt(0)
	v_add_f32_e32 v80, v150, v92
	v_or_b32_sdwa v86, v94, v83 dst_sel:DWORD dst_unused:UNUSED_PAD src0_sel:WORD_1 src1_sel:DWORD
	v_lshlrev_b32_e32 v83, 16, v91
	v_and_or_b32 v91, v95, s4, v81
	ds_bpermute_b32 v81, v208, v80
	v_or_b32_sdwa v84, v88, v84 dst_sel:DWORD dst_unused:UNUSED_PAD src0_sel:WORD_1 src1_sel:DWORD
	v_or_b32_sdwa v85, v89, v85 dst_sel:DWORD dst_unused:UNUSED_PAD src0_sel:WORD_1 src1_sel:DWORD
	v_or_b32_sdwa v87, v95, v93 dst_sel:DWORD dst_unused:UNUSED_PAD src0_sel:WORD_1 src1_sel:DWORD
	v_and_or_b32 v89, v89, s4, v83
	v_and_or_b32 v88, v88, s4, v82
	global_store_dwordx4 v[190:191], v[84:87], off offset:256
	global_store_dwordx4 v[192:193], v[88:91], off offset:256
	s_and_saveexec_b64 s[22:23], s[6:7]
	s_cbranch_execz .LBB0_785
	v_lshlrev_b64 v[82:83], 6, v[186:187]
	s_lshl_b32 s26, s50, 2
	v_lshl_add_u64 v[82:83], s[2:3], 0, v[82:83]
	s_ashr_i32 s27, s26, 31
	v_lshl_add_u64 v[82:83], s[26:27], 2, v[82:83]
	s_lshl_b32 s24, s46, 2
	v_lshl_add_u64 v[82:83], v[82:83], 0, s[24:25]
	s_waitcnt lgkmcnt(0)
	v_add_f32_e32 v80, v80, v81
	global_store_dword v[82:83], v80, off
.LBB0_785:
	s_or_b64 exec, exec, s[22:23]
	v_add_u32_e32 v128, 0x90, v184
	v_ashrrev_i32_e32 v129, 31, v128
	s_waitcnt lgkmcnt(0)
	v_lshlrev_b64 v[80:81], 10, v[128:129]
	v_lshl_add_u64 v[80:81], v[80:81], 0, v[182:183]
	v_readlane_b32 s22, v247, 5
	v_lshlrev_b64 v[80:81], 1, v[80:81]
	v_readlane_b32 s23, v247, 6
	s_nop 1
	v_lshl_add_u64 v[130:131], s[22:23], 0, v[80:81]
	v_readlane_b32 s22, v249, 0
	v_readlane_b32 s23, v249, 1
	global_load_dwordx4 v[88:91], v[130:131], off offset:0
	s_nop 1
	v_lshl_add_u64 v[132:133], s[22:23], 0, v[80:81]
	global_load_dwordx4 v[92:95], v[132:133], off offset:0
	global_load_dwordx4 v[84:87], v[130:131], off offset:256
	global_load_dwordx4 v[80:83], v[132:133], off offset:256
	s_waitcnt vmcnt(16)
	s_nop 0
	v_lshlrev_b32_e32 v134, 16, v121
	v_lshlrev_b32_e32 v136, 16, v120
	v_and_b32_e32 v121, 0xffff0000, v121
	v_and_b32_e32 v120, 0xffff0000, v120
	v_or_b32_sdwa v135, v125, v134 dst_sel:DWORD dst_unused:UNUSED_PAD src0_sel:WORD_0 src1_sel:DWORD
	v_or_b32_sdwa v121, v125, v121 dst_sel:DWORD dst_unused:UNUSED_PAD src0_sel:WORD_1 src1_sel:DWORD
	v_or_b32_sdwa v120, v124, v120 dst_sel:DWORD dst_unused:UNUSED_PAD src0_sel:WORD_1 src1_sel:DWORD
	v_mov_b32_e32 v125, v78
	v_mov_b32_e32 v78, v77
	v_or_b32_sdwa v134, v124, v136 dst_sel:DWORD dst_unused:UNUSED_PAD src0_sel:WORD_0 src1_sel:DWORD
	v_mov_b32_e32 v124, v76
	v_pk_add_f32 v[120:121], v[78:79], v[120:121]
	v_pk_add_f32 v[124:125], v[124:125], v[134:135]
	v_and_b32_e32 v77, 0xffff0000, v120
	v_and_b32_e32 v76, 0xffff0000, v124
	v_mul_f32_e32 v134, v77, v77
	v_fmac_f32_e32 v134, v76, v76
	v_and_b32_e32 v76, 0xffff0000, v125
	v_fmac_f32_e32 v134, v76, v76
	v_and_b32_e32 v78, 0xffff0000, v121
	v_fmac_f32_e32 v134, v78, v78
	v_or_b32_sdwa v76, v124, v77 dst_sel:DWORD dst_unused:UNUSED_PAD src0_sel:WORD_1 src1_sel:DWORD
	v_or_b32_sdwa v77, v125, v78 dst_sel:DWORD dst_unused:UNUSED_PAD src0_sel:WORD_1 src1_sel:DWORD
	v_lshlrev_b32_e32 v78, 16, v123
	v_lshlrev_b32_e32 v135, 16, v122
	v_and_b32_e32 v123, 0xffff0000, v123
	v_and_b32_e32 v122, 0xffff0000, v122
	v_or_b32_sdwa v79, v127, v78 dst_sel:DWORD dst_unused:UNUSED_PAD src0_sel:WORD_0 src1_sel:DWORD
	v_or_b32_sdwa v78, v126, v135 dst_sel:DWORD dst_unused:UNUSED_PAD src0_sel:WORD_0 src1_sel:DWORD
	v_or_b32_sdwa v123, v127, v123 dst_sel:DWORD dst_unused:UNUSED_PAD src0_sel:WORD_1 src1_sel:DWORD
	v_or_b32_sdwa v122, v126, v122 dst_sel:DWORD dst_unused:UNUSED_PAD src0_sel:WORD_1 src1_sel:DWORD
	v_mov_b32_e32 v126, v72
	v_mov_b32_e32 v127, v74
	v_mov_b32_e32 v74, v73
	v_pk_add_f32 v[126:127], v[126:127], v[78:79]
	v_pk_add_f32 v[72:73], v[74:75], v[122:123]
	v_and_b32_e32 v74, 0xffff0000, v126
	v_and_b32_e32 v75, 0xffff0000, v72
	v_and_b32_e32 v123, 0xffff0000, v73
	v_lshlrev_b32_e32 v120, 16, v120
	v_lshlrev_b32_e32 v72, 16, v72
	v_or_b32_sdwa v78, v126, v75 dst_sel:DWORD dst_unused:UNUSED_PAD src0_sel:WORD_1 src1_sel:DWORD
	v_or_b32_sdwa v79, v127, v123 dst_sel:DWORD dst_unused:UNUSED_PAD src0_sel:WORD_1 src1_sel:DWORD
	v_fmac_f32_e32 v134, v74, v74
	v_lshlrev_b32_e32 v121, 16, v121
	v_lshlrev_b32_e32 v73, 16, v73
	v_and_or_b32 v74, v126, s4, v72
	v_and_or_b32 v72, v124, s4, v120
	v_fmac_f32_e32 v134, v75, v75
	v_and_or_b32 v75, v127, s4, v73
	v_and_or_b32 v73, v125, s4, v121
	global_store_dwordx4 v[194:195], v[76:79], off
	global_store_dwordx4 v[196:197], v[72:75], off
	v_and_b32_e32 v122, 0xffff0000, v127
	v_and_b32_e32 v76, 0xffff0000, v116
	v_lshlrev_b32_e32 v72, 16, v117
	v_lshlrev_b32_e32 v74, 16, v116
	v_or_b32_sdwa v73, v113, v72 dst_sel:DWORD dst_unused:UNUSED_PAD src0_sel:WORD_0 src1_sel:DWORD
	v_or_b32_sdwa v72, v112, v74 dst_sel:DWORD dst_unused:UNUSED_PAD src0_sel:WORD_0 src1_sel:DWORD
	v_and_b32_e32 v74, 0xffff0000, v117
	v_or_b32_sdwa v75, v113, v74 dst_sel:DWORD dst_unused:UNUSED_PAD src0_sel:WORD_1 src1_sel:DWORD
	v_or_b32_sdwa v74, v112, v76 dst_sel:DWORD dst_unused:UNUSED_PAD src0_sel:WORD_1 src1_sel:DWORD
	v_mov_b32_e32 v76, v68
	v_mov_b32_e32 v77, v70
	v_fmac_f32_e32 v134, v122, v122
	v_pk_add_f32 v[72:73], v[76:77], v[72:73]
	v_mov_b32_e32 v70, v69
	v_fmac_f32_e32 v134, v123, v123
	v_pk_add_f32 v[74:75], v[70:71], v[74:75]
	v_and_b32_e32 v68, 0xffff0000, v72
	v_lshlrev_b32_e32 v70, 16, v119
	v_lshlrev_b32_e32 v76, 16, v118
	v_fmac_f32_e32 v134, v68, v68
	v_and_b32_e32 v68, 0xffff0000, v74
	v_or_b32_sdwa v71, v115, v70 dst_sel:DWORD dst_unused:UNUSED_PAD src0_sel:WORD_0 src1_sel:DWORD
	v_or_b32_sdwa v70, v114, v76 dst_sel:DWORD dst_unused:UNUSED_PAD src0_sel:WORD_0 src1_sel:DWORD
	v_and_b32_e32 v76, 0xffff0000, v119
	v_and_b32_e32 v78, 0xffff0000, v118
	v_fmac_f32_e32 v134, v68, v68
	v_and_b32_e32 v69, 0xffff0000, v73
	v_or_b32_sdwa v77, v115, v76 dst_sel:DWORD dst_unused:UNUSED_PAD src0_sel:WORD_1 src1_sel:DWORD
	v_or_b32_sdwa v76, v114, v78 dst_sel:DWORD dst_unused:UNUSED_PAD src0_sel:WORD_1 src1_sel:DWORD
	v_mov_b32_e32 v78, v64
	v_mov_b32_e32 v79, v66
	v_fmac_f32_e32 v134, v69, v69
	v_and_b32_e32 v69, 0xffff0000, v75
	v_pk_add_f32 v[78:79], v[78:79], v[70:71]
	v_mov_b32_e32 v66, v65
	v_fmac_f32_e32 v134, v69, v69
	v_pk_add_f32 v[64:65], v[66:67], v[76:77]
	v_and_b32_e32 v66, 0xffff0000, v78
	v_and_b32_e32 v67, 0xffff0000, v64
	v_fmac_f32_e32 v134, v66, v66
	v_and_b32_e32 v76, 0xffff0000, v79
	v_fmac_f32_e32 v134, v67, v67
	v_and_b32_e32 v77, 0xffff0000, v65
	v_fmac_f32_e32 v134, v76, v76
	v_fmac_f32_e32 v134, v77, v77
	ds_bpermute_b32 v76, v207, v134
	v_lshlrev_b32_e32 v64, 16, v64
	v_lshlrev_b32_e32 v66, 16, v74
	v_lshlrev_b32_e32 v65, 16, v65
	v_and_or_b32 v74, v78, s4, v64
	s_waitcnt lgkmcnt(0)
	v_add_f32_e32 v64, v134, v76
	v_or_b32_sdwa v70, v78, v67 dst_sel:DWORD dst_unused:UNUSED_PAD src0_sel:WORD_1 src1_sel:DWORD
	v_lshlrev_b32_e32 v67, 16, v75
	v_and_or_b32 v75, v79, s4, v65
	ds_bpermute_b32 v65, v208, v64
	v_or_b32_sdwa v68, v72, v68 dst_sel:DWORD dst_unused:UNUSED_PAD src0_sel:WORD_1 src1_sel:DWORD
	v_or_b32_sdwa v69, v73, v69 dst_sel:DWORD dst_unused:UNUSED_PAD src0_sel:WORD_1 src1_sel:DWORD
	v_or_b32_sdwa v71, v79, v77 dst_sel:DWORD dst_unused:UNUSED_PAD src0_sel:WORD_1 src1_sel:DWORD
	v_and_or_b32 v73, v73, s4, v67
	v_and_or_b32 v72, v72, s4, v66
	global_store_dwordx4 v[194:195], v[68:71], off offset:256
	global_store_dwordx4 v[196:197], v[72:75], off offset:256
	s_and_saveexec_b64 s[22:23], s[6:7]
	s_cbranch_execz .LBB0_787
	v_lshlrev_b64 v[66:67], 6, v[188:189]
	s_lshl_b32 s26, s50, 2
	v_lshl_add_u64 v[66:67], s[2:3], 0, v[66:67]
	s_ashr_i32 s27, s26, 31
	v_lshl_add_u64 v[66:67], s[26:27], 2, v[66:67]
	s_lshl_b32 s24, s46, 2
	v_lshl_add_u64 v[66:67], v[66:67], 0, s[24:25]
	s_waitcnt lgkmcnt(0)
	v_add_f32_e32 v64, v64, v65
	global_store_dword v[66:67], v64, off
.LBB0_787:
	s_or_b64 exec, exec, s[22:23]
	v_add_u32_e32 v112, 0xa0, v184
	v_ashrrev_i32_e32 v113, 31, v112
	s_waitcnt lgkmcnt(0)
	v_lshlrev_b64 v[64:65], 10, v[112:113]
	v_lshl_add_u64 v[64:65], v[64:65], 0, v[182:183]
	v_readlane_b32 s22, v247, 5
	v_lshlrev_b64 v[64:65], 1, v[64:65]
	v_readlane_b32 s23, v247, 6
	s_nop 1
	v_lshl_add_u64 v[114:115], s[22:23], 0, v[64:65]
	v_readlane_b32 s22, v249, 0
	v_readlane_b32 s23, v249, 1
	global_load_dwordx4 v[72:75], v[114:115], off offset:0
	s_nop 1
	v_lshl_add_u64 v[116:117], s[22:23], 0, v[64:65]
	global_load_dwordx4 v[76:79], v[116:117], off offset:0
	global_load_dwordx4 v[68:71], v[114:115], off offset:256
	global_load_dwordx4 v[64:67], v[116:117], off offset:256
	s_waitcnt vmcnt(16)
	s_nop 0
	v_lshlrev_b32_e32 v118, 16, v105
	v_lshlrev_b32_e32 v120, 16, v104
	v_and_b32_e32 v105, 0xffff0000, v105
	v_and_b32_e32 v104, 0xffff0000, v104
	v_or_b32_sdwa v119, v109, v118 dst_sel:DWORD dst_unused:UNUSED_PAD src0_sel:WORD_0 src1_sel:DWORD
	v_or_b32_sdwa v105, v109, v105 dst_sel:DWORD dst_unused:UNUSED_PAD src0_sel:WORD_1 src1_sel:DWORD
	v_or_b32_sdwa v104, v108, v104 dst_sel:DWORD dst_unused:UNUSED_PAD src0_sel:WORD_1 src1_sel:DWORD
	v_mov_b32_e32 v109, v62
	v_mov_b32_e32 v62, v61
	v_or_b32_sdwa v118, v108, v120 dst_sel:DWORD dst_unused:UNUSED_PAD src0_sel:WORD_0 src1_sel:DWORD
	v_mov_b32_e32 v108, v60
	v_pk_add_f32 v[104:105], v[62:63], v[104:105]
	v_pk_add_f32 v[108:109], v[108:109], v[118:119]
	v_and_b32_e32 v61, 0xffff0000, v104
	v_and_b32_e32 v60, 0xffff0000, v108
	v_mul_f32_e32 v118, v61, v61
	v_fmac_f32_e32 v118, v60, v60
	v_and_b32_e32 v60, 0xffff0000, v109
	v_fmac_f32_e32 v118, v60, v60
	v_and_b32_e32 v62, 0xffff0000, v105
	v_fmac_f32_e32 v118, v62, v62
	v_or_b32_sdwa v60, v61, v108 dst_sel:DWORD dst_unused:UNUSED_PAD src0_sel:DWORD src1_sel:WORD_1
	v_or_b32_sdwa v61, v62, v109 dst_sel:DWORD dst_unused:UNUSED_PAD src0_sel:DWORD src1_sel:WORD_1
	v_lshlrev_b32_e32 v62, 16, v107
	v_lshlrev_b32_e32 v119, 16, v106
	v_and_b32_e32 v107, 0xffff0000, v107
	v_and_b32_e32 v106, 0xffff0000, v106
	v_or_b32_sdwa v63, v111, v62 dst_sel:DWORD dst_unused:UNUSED_PAD src0_sel:WORD_0 src1_sel:DWORD
	v_or_b32_sdwa v62, v110, v119 dst_sel:DWORD dst_unused:UNUSED_PAD src0_sel:WORD_0 src1_sel:DWORD
	v_or_b32_sdwa v107, v111, v107 dst_sel:DWORD dst_unused:UNUSED_PAD src0_sel:WORD_1 src1_sel:DWORD
	v_or_b32_sdwa v106, v110, v106 dst_sel:DWORD dst_unused:UNUSED_PAD src0_sel:WORD_1 src1_sel:DWORD
	v_mov_b32_e32 v110, v56
	v_mov_b32_e32 v111, v58
	v_pk_add_f32 v[110:111], v[110:111], v[62:63]
	v_mov_b32_e32 v58, v57
	v_pk_add_f32 v[56:57], v[58:59], v[106:107]
	v_and_b32_e32 v58, 0xffff0000, v110
	v_and_b32_e32 v59, 0xffff0000, v56
	v_fmac_f32_e32 v118, v58, v58
	v_and_b32_e32 v106, 0xffff0000, v111
	v_fmac_f32_e32 v118, v59, v59
	v_and_b32_e32 v107, 0xffff0000, v57
	v_fmac_f32_e32 v118, v106, v106
	v_and_b32_e32 v106, 0xffff, v108
	v_and_b32_e32 v58, 0xffff, v110
	v_or_b32_sdwa v62, v59, v110 dst_sel:DWORD dst_unused:UNUSED_PAD src0_sel:DWORD src1_sel:WORD_1
	v_or_b32_sdwa v63, v107, v111 dst_sel:DWORD dst_unused:UNUSED_PAD src0_sel:DWORD src1_sel:WORD_1
	v_fmac_f32_e32 v118, v107, v107
	v_and_b32_e32 v107, 0xffff, v109
	v_and_b32_e32 v59, 0xffff, v111
	v_lshl_or_b32 v58, v56, 16, v58
	v_lshl_or_b32 v56, v104, 16, v106
	v_lshl_or_b32 v59, v57, 16, v59
	v_lshl_or_b32 v57, v105, 16, v107
	global_store_dwordx4 v[146:147], v[60:63], off
	global_store_dwordx4 v[148:149], v[56:59], off
	s_nop 0
	v_and_b32_e32 v60, 0xffff0000, v100
	v_lshlrev_b32_e32 v56, 16, v101
	v_lshlrev_b32_e32 v58, 16, v100
	v_or_b32_sdwa v57, v97, v56 dst_sel:DWORD dst_unused:UNUSED_PAD src0_sel:WORD_0 src1_sel:DWORD
	v_or_b32_sdwa v56, v96, v58 dst_sel:DWORD dst_unused:UNUSED_PAD src0_sel:WORD_0 src1_sel:DWORD
	v_and_b32_e32 v58, 0xffff0000, v101
	v_or_b32_sdwa v59, v97, v58 dst_sel:DWORD dst_unused:UNUSED_PAD src0_sel:WORD_1 src1_sel:DWORD
	v_or_b32_sdwa v58, v96, v60 dst_sel:DWORD dst_unused:UNUSED_PAD src0_sel:WORD_1 src1_sel:DWORD
	v_mov_b32_e32 v60, v52
	v_mov_b32_e32 v61, v54
	v_pk_add_f32 v[56:57], v[60:61], v[56:57]
	v_mov_b32_e32 v54, v53
	v_pk_add_f32 v[60:61], v[54:55], v[58:59]
	v_and_b32_e32 v52, 0xffff0000, v56
	v_lshlrev_b32_e32 v54, 16, v103
	v_lshlrev_b32_e32 v58, 16, v102
	v_fmac_f32_e32 v118, v52, v52
	v_and_b32_e32 v52, 0xffff0000, v60
	v_or_b32_sdwa v55, v99, v54 dst_sel:DWORD dst_unused:UNUSED_PAD src0_sel:WORD_0 src1_sel:DWORD
	v_or_b32_sdwa v54, v98, v58 dst_sel:DWORD dst_unused:UNUSED_PAD src0_sel:WORD_0 src1_sel:DWORD
	v_and_b32_e32 v58, 0xffff0000, v103
	v_and_b32_e32 v62, 0xffff0000, v102
	v_fmac_f32_e32 v118, v52, v52
	v_and_b32_e32 v53, 0xffff0000, v57
	v_or_b32_sdwa v59, v99, v58 dst_sel:DWORD dst_unused:UNUSED_PAD src0_sel:WORD_1 src1_sel:DWORD
	v_or_b32_sdwa v58, v98, v62 dst_sel:DWORD dst_unused:UNUSED_PAD src0_sel:WORD_1 src1_sel:DWORD
	v_mov_b32_e32 v62, v48
	v_mov_b32_e32 v63, v50
	v_fmac_f32_e32 v118, v53, v53
	v_and_b32_e32 v53, 0xffff0000, v61
	v_pk_add_f32 v[62:63], v[62:63], v[54:55]
	v_mov_b32_e32 v50, v49
	v_fmac_f32_e32 v118, v53, v53
	v_pk_add_f32 v[48:49], v[50:51], v[58:59]
	v_and_b32_e32 v50, 0xffff0000, v62
	v_and_b32_e32 v51, 0xffff0000, v48
	v_fmac_f32_e32 v118, v50, v50
	v_and_b32_e32 v58, 0xffff0000, v63
	v_fmac_f32_e32 v118, v51, v51
	v_and_b32_e32 v59, 0xffff0000, v49
	v_fmac_f32_e32 v118, v58, v58
	v_fmac_f32_e32 v118, v59, v59
	v_or_b32_sdwa v52, v52, v56 dst_sel:DWORD dst_unused:UNUSED_PAD src0_sel:DWORD src1_sel:WORD_1
	v_and_b32_e32 v50, 0xffff, v56
	ds_bpermute_b32 v56, v207, v118
	v_or_b32_sdwa v53, v53, v57 dst_sel:DWORD dst_unused:UNUSED_PAD src0_sel:DWORD src1_sel:WORD_1
	v_or_b32_sdwa v54, v51, v62 dst_sel:DWORD dst_unused:UNUSED_PAD src0_sel:DWORD src1_sel:WORD_1
	v_and_b32_e32 v51, 0xffff, v57
	v_and_b32_e32 v57, 0xffff, v62
	v_and_b32_e32 v58, 0xffff, v63
	v_or_b32_sdwa v55, v59, v63 dst_sel:DWORD dst_unused:UNUSED_PAD src0_sel:DWORD src1_sel:WORD_1
	v_lshl_or_b32 v59, v49, 16, v58
	v_lshl_or_b32 v58, v48, 16, v57
	s_waitcnt lgkmcnt(0)
	v_add_f32_e32 v48, v118, v56
	ds_bpermute_b32 v49, v208, v48
	v_lshl_or_b32 v57, v61, 16, v51
	v_lshl_or_b32 v56, v60, 16, v50
	global_store_dwordx4 v[146:147], v[52:55], off offset:256
	global_store_dwordx4 v[148:149], v[56:59], off offset:256
	s_and_saveexec_b64 s[22:23], s[6:7]
	s_cbranch_execz .LBB0_789
	v_lshlrev_b64 v[50:51], 6, v[144:145]
	s_lshl_b32 s26, s50, 2
	v_lshl_add_u64 v[50:51], s[2:3], 0, v[50:51]
	s_ashr_i32 s27, s26, 31
	v_lshl_add_u64 v[50:51], s[26:27], 2, v[50:51]
	s_lshl_b32 s24, s46, 2
	v_lshl_add_u64 v[50:51], v[50:51], 0, s[24:25]
	s_waitcnt lgkmcnt(0)
	v_add_f32_e32 v48, v48, v49
	global_store_dword v[50:51], v48, off
.LBB0_789:
	s_or_b64 exec, exec, s[22:23]
	v_add_u32_e32 v96, 0xb0, v184
	v_ashrrev_i32_e32 v97, 31, v96
	s_waitcnt lgkmcnt(0)
	v_lshlrev_b64 v[48:49], 10, v[96:97]
	v_lshl_add_u64 v[48:49], v[48:49], 0, v[182:183]
	v_readlane_b32 s22, v247, 5
	v_lshlrev_b64 v[48:49], 1, v[48:49]
	v_readlane_b32 s23, v247, 6
	s_nop 1
	v_lshl_add_u64 v[98:99], s[22:23], 0, v[48:49]
	v_readlane_b32 s22, v249, 0
	v_readlane_b32 s23, v249, 1
	global_load_dwordx4 v[56:59], v[98:99], off offset:0
	s_nop 1
	v_lshl_add_u64 v[100:101], s[22:23], 0, v[48:49]
	global_load_dwordx4 v[60:63], v[100:101], off offset:0
	global_load_dwordx4 v[52:55], v[98:99], off offset:256
	global_load_dwordx4 v[48:51], v[100:101], off offset:256
	s_waitcnt vmcnt(16)
	s_nop 0
	v_lshlrev_b32_e32 v102, 16, v89
	v_lshlrev_b32_e32 v104, 16, v88
	v_and_b32_e32 v89, 0xffff0000, v89
	v_and_b32_e32 v88, 0xffff0000, v88
	v_or_b32_sdwa v103, v93, v102 dst_sel:DWORD dst_unused:UNUSED_PAD src0_sel:WORD_0 src1_sel:DWORD
	v_or_b32_sdwa v89, v93, v89 dst_sel:DWORD dst_unused:UNUSED_PAD src0_sel:WORD_1 src1_sel:DWORD
	v_or_b32_sdwa v88, v92, v88 dst_sel:DWORD dst_unused:UNUSED_PAD src0_sel:WORD_1 src1_sel:DWORD
	v_mov_b32_e32 v93, v46
	v_mov_b32_e32 v46, v45
	v_or_b32_sdwa v102, v92, v104 dst_sel:DWORD dst_unused:UNUSED_PAD src0_sel:WORD_0 src1_sel:DWORD
	v_mov_b32_e32 v92, v44
	v_pk_add_f32 v[88:89], v[46:47], v[88:89]
	v_pk_add_f32 v[92:93], v[92:93], v[102:103]
	v_and_b32_e32 v45, 0xffff0000, v88
	v_and_b32_e32 v44, 0xffff0000, v92
	v_mul_f32_e32 v102, v45, v45
	v_fmac_f32_e32 v102, v44, v44
	v_and_b32_e32 v44, 0xffff0000, v93
	v_fmac_f32_e32 v102, v44, v44
	v_and_b32_e32 v46, 0xffff0000, v89
	v_fmac_f32_e32 v102, v46, v46
	v_or_b32_sdwa v44, v45, v92 dst_sel:DWORD dst_unused:UNUSED_PAD src0_sel:DWORD src1_sel:WORD_1
	v_or_b32_sdwa v45, v46, v93 dst_sel:DWORD dst_unused:UNUSED_PAD src0_sel:DWORD src1_sel:WORD_1
	v_lshlrev_b32_e32 v46, 16, v91
	v_lshlrev_b32_e32 v103, 16, v90
	v_and_b32_e32 v91, 0xffff0000, v91
	v_and_b32_e32 v90, 0xffff0000, v90
	v_or_b32_sdwa v47, v95, v46 dst_sel:DWORD dst_unused:UNUSED_PAD src0_sel:WORD_0 src1_sel:DWORD
	v_or_b32_sdwa v46, v94, v103 dst_sel:DWORD dst_unused:UNUSED_PAD src0_sel:WORD_0 src1_sel:DWORD
	v_or_b32_sdwa v91, v95, v91 dst_sel:DWORD dst_unused:UNUSED_PAD src0_sel:WORD_1 src1_sel:DWORD
	v_or_b32_sdwa v90, v94, v90 dst_sel:DWORD dst_unused:UNUSED_PAD src0_sel:WORD_1 src1_sel:DWORD
	v_mov_b32_e32 v94, v40
	v_mov_b32_e32 v95, v42
	v_pk_add_f32 v[94:95], v[94:95], v[46:47]
	v_mov_b32_e32 v42, v41
	v_pk_add_f32 v[40:41], v[42:43], v[90:91]
	v_and_b32_e32 v42, 0xffff0000, v94
	v_and_b32_e32 v43, 0xffff0000, v40
	v_fmac_f32_e32 v102, v42, v42
	v_and_b32_e32 v90, 0xffff0000, v95
	v_fmac_f32_e32 v102, v43, v43
	v_and_b32_e32 v91, 0xffff0000, v41
	v_fmac_f32_e32 v102, v90, v90
	v_and_b32_e32 v90, 0xffff, v92
	v_and_b32_e32 v42, 0xffff, v94
	v_or_b32_sdwa v46, v43, v94 dst_sel:DWORD dst_unused:UNUSED_PAD src0_sel:DWORD src1_sel:WORD_1
	v_or_b32_sdwa v47, v91, v95 dst_sel:DWORD dst_unused:UNUSED_PAD src0_sel:DWORD src1_sel:WORD_1
	v_fmac_f32_e32 v102, v91, v91
	v_and_b32_e32 v91, 0xffff, v93
	v_and_b32_e32 v43, 0xffff, v95
	v_lshl_or_b32 v42, v40, 16, v42
	v_lshl_or_b32 v40, v88, 16, v90
	v_lshl_or_b32 v43, v41, 16, v43
	v_lshl_or_b32 v41, v89, 16, v91
	global_store_dwordx4 v[130:131], v[44:47], off
	global_store_dwordx4 v[132:133], v[40:43], off
	s_nop 0
	v_and_b32_e32 v44, 0xffff0000, v84
	v_lshlrev_b32_e32 v40, 16, v85
	v_lshlrev_b32_e32 v42, 16, v84
	v_or_b32_sdwa v41, v81, v40 dst_sel:DWORD dst_unused:UNUSED_PAD src0_sel:WORD_0 src1_sel:DWORD
	v_or_b32_sdwa v40, v80, v42 dst_sel:DWORD dst_unused:UNUSED_PAD src0_sel:WORD_0 src1_sel:DWORD
	v_and_b32_e32 v42, 0xffff0000, v85
	v_or_b32_sdwa v43, v81, v42 dst_sel:DWORD dst_unused:UNUSED_PAD src0_sel:WORD_1 src1_sel:DWORD
	v_or_b32_sdwa v42, v80, v44 dst_sel:DWORD dst_unused:UNUSED_PAD src0_sel:WORD_1 src1_sel:DWORD
	v_mov_b32_e32 v44, v36
	v_mov_b32_e32 v45, v38
	v_pk_add_f32 v[40:41], v[44:45], v[40:41]
	v_mov_b32_e32 v38, v37
	v_pk_add_f32 v[44:45], v[38:39], v[42:43]
	v_and_b32_e32 v36, 0xffff0000, v40
	v_lshlrev_b32_e32 v38, 16, v87
	v_lshlrev_b32_e32 v42, 16, v86
	v_fmac_f32_e32 v102, v36, v36
	v_and_b32_e32 v36, 0xffff0000, v44
	v_or_b32_sdwa v39, v83, v38 dst_sel:DWORD dst_unused:UNUSED_PAD src0_sel:WORD_0 src1_sel:DWORD
	v_or_b32_sdwa v38, v82, v42 dst_sel:DWORD dst_unused:UNUSED_PAD src0_sel:WORD_0 src1_sel:DWORD
	v_and_b32_e32 v42, 0xffff0000, v87
	v_and_b32_e32 v46, 0xffff0000, v86
	v_fmac_f32_e32 v102, v36, v36
	v_and_b32_e32 v37, 0xffff0000, v41
	v_or_b32_sdwa v43, v83, v42 dst_sel:DWORD dst_unused:UNUSED_PAD src0_sel:WORD_1 src1_sel:DWORD
	v_or_b32_sdwa v42, v82, v46 dst_sel:DWORD dst_unused:UNUSED_PAD src0_sel:WORD_1 src1_sel:DWORD
	v_mov_b32_e32 v46, v32
	v_mov_b32_e32 v47, v34
	v_fmac_f32_e32 v102, v37, v37
	v_and_b32_e32 v37, 0xffff0000, v45
	v_pk_add_f32 v[46:47], v[46:47], v[38:39]
	v_mov_b32_e32 v34, v33
	v_fmac_f32_e32 v102, v37, v37
	v_pk_add_f32 v[32:33], v[34:35], v[42:43]
	v_and_b32_e32 v34, 0xffff0000, v46
	v_and_b32_e32 v35, 0xffff0000, v32
	v_fmac_f32_e32 v102, v34, v34
	v_and_b32_e32 v42, 0xffff0000, v47
	v_fmac_f32_e32 v102, v35, v35
	v_and_b32_e32 v43, 0xffff0000, v33
	v_fmac_f32_e32 v102, v42, v42
	v_fmac_f32_e32 v102, v43, v43
	v_or_b32_sdwa v36, v36, v40 dst_sel:DWORD dst_unused:UNUSED_PAD src0_sel:DWORD src1_sel:WORD_1
	v_and_b32_e32 v34, 0xffff, v40
	ds_bpermute_b32 v40, v207, v102
	v_or_b32_sdwa v37, v37, v41 dst_sel:DWORD dst_unused:UNUSED_PAD src0_sel:DWORD src1_sel:WORD_1
	v_or_b32_sdwa v38, v35, v46 dst_sel:DWORD dst_unused:UNUSED_PAD src0_sel:DWORD src1_sel:WORD_1
	v_and_b32_e32 v35, 0xffff, v41
	v_and_b32_e32 v41, 0xffff, v46
	v_and_b32_e32 v42, 0xffff, v47
	v_or_b32_sdwa v39, v43, v47 dst_sel:DWORD dst_unused:UNUSED_PAD src0_sel:DWORD src1_sel:WORD_1
	v_lshl_or_b32 v43, v33, 16, v42
	v_lshl_or_b32 v42, v32, 16, v41
	s_waitcnt lgkmcnt(0)
	v_add_f32_e32 v32, v102, v40
	ds_bpermute_b32 v33, v208, v32
	v_lshl_or_b32 v41, v45, 16, v35
	v_lshl_or_b32 v40, v44, 16, v34
	global_store_dwordx4 v[130:131], v[36:39], off offset:256
	global_store_dwordx4 v[132:133], v[40:43], off offset:256
	s_and_saveexec_b64 s[22:23], s[6:7]
	s_cbranch_execz .LBB0_791
	v_lshlrev_b64 v[34:35], 6, v[128:129]
	s_lshl_b32 s26, s50, 2
	v_lshl_add_u64 v[34:35], s[2:3], 0, v[34:35]
	s_ashr_i32 s27, s26, 31
	v_lshl_add_u64 v[34:35], s[26:27], 2, v[34:35]
	s_lshl_b32 s24, s46, 2
	v_lshl_add_u64 v[34:35], v[34:35], 0, s[24:25]
	s_waitcnt lgkmcnt(0)
	v_add_f32_e32 v32, v32, v33
	global_store_dword v[34:35], v32, off
.LBB0_791:
	s_or_b64 exec, exec, s[22:23]
	s_waitcnt vmcnt(12)
	v_mov_b32_e32 v37, v30
	v_lshlrev_b32_e32 v32, 16, v73
	v_lshlrev_b32_e32 v34, 16, v72
	v_and_b32_e32 v35, 0xffff0000, v73
	s_waitcnt lgkmcnt(0)
	v_or_b32_sdwa v33, v77, v32 dst_sel:DWORD dst_unused:UNUSED_PAD src0_sel:WORD_0 src1_sel:DWORD
	v_or_b32_sdwa v32, v76, v34 dst_sel:DWORD dst_unused:UNUSED_PAD src0_sel:WORD_0 src1_sel:DWORD
	v_and_b32_e32 v34, 0xffff0000, v72
	v_or_b32_sdwa v35, v77, v35 dst_sel:DWORD dst_unused:UNUSED_PAD src0_sel:WORD_1 src1_sel:DWORD
	v_or_b32_sdwa v34, v76, v34 dst_sel:DWORD dst_unused:UNUSED_PAD src0_sel:WORD_1 src1_sel:DWORD
	v_mov_b32_e32 v30, v29
	v_mov_b32_e32 v36, v28
	v_pk_add_f32 v[34:35], v[30:31], v[34:35]
	v_pk_add_f32 v[32:33], v[36:37], v[32:33]
	v_and_b32_e32 v29, 0xffff0000, v34
	v_and_b32_e32 v28, 0xffff0000, v32
	v_mul_f32_e32 v40, v29, v29
	v_fmac_f32_e32 v40, v28, v28
	v_and_b32_e32 v28, 0xffff0000, v33
	v_fmac_f32_e32 v40, v28, v28
	v_and_b32_e32 v30, 0xffff0000, v35
	v_fmac_f32_e32 v40, v30, v30
	v_or_b32_sdwa v28, v29, v32 dst_sel:DWORD dst_unused:UNUSED_PAD src0_sel:DWORD src1_sel:WORD_1
	v_or_b32_sdwa v29, v30, v33 dst_sel:DWORD dst_unused:UNUSED_PAD src0_sel:DWORD src1_sel:WORD_1
	v_lshlrev_b32_e32 v30, 16, v75
	v_lshlrev_b32_e32 v36, 16, v74
	v_or_b32_sdwa v31, v79, v30 dst_sel:DWORD dst_unused:UNUSED_PAD src0_sel:WORD_0 src1_sel:DWORD
	v_or_b32_sdwa v30, v78, v36 dst_sel:DWORD dst_unused:UNUSED_PAD src0_sel:WORD_0 src1_sel:DWORD
	v_and_b32_e32 v36, 0xffff0000, v75
	v_and_b32_e32 v38, 0xffff0000, v74
	v_or_b32_sdwa v37, v79, v36 dst_sel:DWORD dst_unused:UNUSED_PAD src0_sel:WORD_1 src1_sel:DWORD
	v_or_b32_sdwa v36, v78, v38 dst_sel:DWORD dst_unused:UNUSED_PAD src0_sel:WORD_1 src1_sel:DWORD
	v_mov_b32_e32 v38, v24
	v_mov_b32_e32 v39, v26
	v_pk_add_f32 v[38:39], v[38:39], v[30:31]
	v_mov_b32_e32 v26, v25
	v_pk_add_f32 v[24:25], v[26:27], v[36:37]
	v_and_b32_e32 v26, 0xffff0000, v38
	v_and_b32_e32 v27, 0xffff0000, v24
	v_and_b32_e32 v37, 0xffff0000, v25
	v_fmac_f32_e32 v40, v26, v26
	v_and_b32_e32 v32, 0xffff, v32
	v_and_b32_e32 v26, 0xffff, v38
	v_or_b32_sdwa v30, v27, v38 dst_sel:DWORD dst_unused:UNUSED_PAD src0_sel:DWORD src1_sel:WORD_1
	v_or_b32_sdwa v31, v37, v39 dst_sel:DWORD dst_unused:UNUSED_PAD src0_sel:DWORD src1_sel:WORD_1
	v_fmac_f32_e32 v40, v27, v27
	v_and_b32_e32 v33, 0xffff, v33
	v_and_b32_e32 v27, 0xffff, v39
	v_lshl_or_b32 v26, v24, 16, v26
	v_lshl_or_b32 v24, v34, 16, v32
	v_lshl_or_b32 v27, v25, 16, v27
	v_lshl_or_b32 v25, v35, 16, v33
	global_store_dwordx4 v[114:115], v[28:31], off
	global_store_dwordx4 v[116:117], v[24:27], off
	v_and_b32_e32 v36, 0xffff0000, v39
	v_and_b32_e32 v28, 0xffff0000, v68
	v_lshlrev_b32_e32 v24, 16, v69
	v_lshlrev_b32_e32 v26, 16, v68
	v_or_b32_sdwa v25, v65, v24 dst_sel:DWORD dst_unused:UNUSED_PAD src0_sel:WORD_0 src1_sel:DWORD
	v_or_b32_sdwa v24, v64, v26 dst_sel:DWORD dst_unused:UNUSED_PAD src0_sel:WORD_0 src1_sel:DWORD
	v_and_b32_e32 v26, 0xffff0000, v69
	v_or_b32_sdwa v27, v65, v26 dst_sel:DWORD dst_unused:UNUSED_PAD src0_sel:WORD_1 src1_sel:DWORD
	v_or_b32_sdwa v26, v64, v28 dst_sel:DWORD dst_unused:UNUSED_PAD src0_sel:WORD_1 src1_sel:DWORD
	v_mov_b32_e32 v28, v20
	v_mov_b32_e32 v29, v22
	v_fmac_f32_e32 v40, v36, v36
	v_pk_add_f32 v[24:25], v[28:29], v[24:25]
	v_mov_b32_e32 v22, v21
	v_fmac_f32_e32 v40, v37, v37
	v_pk_add_f32 v[28:29], v[22:23], v[26:27]
	v_and_b32_e32 v20, 0xffff0000, v24
	v_lshlrev_b32_e32 v22, 16, v71
	v_lshlrev_b32_e32 v26, 16, v70
	v_fmac_f32_e32 v40, v20, v20
	v_and_b32_e32 v20, 0xffff0000, v28
	v_or_b32_sdwa v23, v67, v22 dst_sel:DWORD dst_unused:UNUSED_PAD src0_sel:WORD_0 src1_sel:DWORD
	v_or_b32_sdwa v22, v66, v26 dst_sel:DWORD dst_unused:UNUSED_PAD src0_sel:WORD_0 src1_sel:DWORD
	v_and_b32_e32 v26, 0xffff0000, v71
	v_and_b32_e32 v30, 0xffff0000, v70
	v_fmac_f32_e32 v40, v20, v20
	v_and_b32_e32 v21, 0xffff0000, v25
	v_or_b32_sdwa v27, v67, v26 dst_sel:DWORD dst_unused:UNUSED_PAD src0_sel:WORD_1 src1_sel:DWORD
	v_or_b32_sdwa v26, v66, v30 dst_sel:DWORD dst_unused:UNUSED_PAD src0_sel:WORD_1 src1_sel:DWORD
	v_mov_b32_e32 v30, v16
	v_mov_b32_e32 v31, v18
	v_fmac_f32_e32 v40, v21, v21
	v_and_b32_e32 v21, 0xffff0000, v29
	v_pk_add_f32 v[30:31], v[30:31], v[22:23]
	v_mov_b32_e32 v18, v17
	v_fmac_f32_e32 v40, v21, v21
	v_pk_add_f32 v[16:17], v[18:19], v[26:27]
	v_and_b32_e32 v18, 0xffff0000, v30
	v_and_b32_e32 v19, 0xffff0000, v16
	v_fmac_f32_e32 v40, v18, v18
	v_and_b32_e32 v26, 0xffff0000, v31
	v_fmac_f32_e32 v40, v19, v19
	v_and_b32_e32 v27, 0xffff0000, v17
	v_fmac_f32_e32 v40, v26, v26
	v_fmac_f32_e32 v40, v27, v27
	v_or_b32_sdwa v20, v20, v24 dst_sel:DWORD dst_unused:UNUSED_PAD src0_sel:DWORD src1_sel:WORD_1
	v_and_b32_e32 v18, 0xffff, v24
	ds_bpermute_b32 v24, v207, v40
	v_or_b32_sdwa v21, v21, v25 dst_sel:DWORD dst_unused:UNUSED_PAD src0_sel:DWORD src1_sel:WORD_1
	v_or_b32_sdwa v22, v19, v30 dst_sel:DWORD dst_unused:UNUSED_PAD src0_sel:DWORD src1_sel:WORD_1
	v_and_b32_e32 v19, 0xffff, v25
	v_and_b32_e32 v25, 0xffff, v30
	v_and_b32_e32 v26, 0xffff, v31
	v_or_b32_sdwa v23, v27, v31 dst_sel:DWORD dst_unused:UNUSED_PAD src0_sel:DWORD src1_sel:WORD_1
	v_lshl_or_b32 v27, v17, 16, v26
	v_lshl_or_b32 v26, v16, 16, v25
	s_waitcnt lgkmcnt(0)
	v_add_f32_e32 v16, v40, v24
	ds_bpermute_b32 v17, v208, v16
	v_lshl_or_b32 v25, v29, 16, v19
	v_lshl_or_b32 v24, v28, 16, v18
	global_store_dwordx4 v[114:115], v[20:23], off offset:256
	global_store_dwordx4 v[116:117], v[24:27], off offset:256
	s_and_saveexec_b64 s[22:23], s[6:7]
	s_cbranch_execz .LBB0_793
	v_lshlrev_b64 v[18:19], 6, v[112:113]
	s_lshl_b32 s26, s50, 2
	v_lshl_add_u64 v[18:19], s[2:3], 0, v[18:19]
	s_ashr_i32 s27, s26, 31
	v_lshl_add_u64 v[18:19], s[26:27], 2, v[18:19]
	s_lshl_b32 s24, s46, 2
	v_lshl_add_u64 v[18:19], v[18:19], 0, s[24:25]
	s_waitcnt lgkmcnt(0)
	v_add_f32_e32 v16, v16, v17
	global_store_dword v[18:19], v16, off
.LBB0_793:
	s_or_b64 exec, exec, s[22:23]
	s_waitcnt vmcnt(8)
	v_mov_b32_e32 v21, v14
	v_lshlrev_b32_e32 v16, 16, v57
	v_lshlrev_b32_e32 v18, 16, v56
	v_and_b32_e32 v19, 0xffff0000, v57
	s_waitcnt lgkmcnt(0)
	v_or_b32_sdwa v17, v61, v16 dst_sel:DWORD dst_unused:UNUSED_PAD src0_sel:WORD_0 src1_sel:DWORD
	v_or_b32_sdwa v16, v60, v18 dst_sel:DWORD dst_unused:UNUSED_PAD src0_sel:WORD_0 src1_sel:DWORD
	v_and_b32_e32 v18, 0xffff0000, v56
	v_or_b32_sdwa v19, v61, v19 dst_sel:DWORD dst_unused:UNUSED_PAD src0_sel:WORD_1 src1_sel:DWORD
	v_or_b32_sdwa v18, v60, v18 dst_sel:DWORD dst_unused:UNUSED_PAD src0_sel:WORD_1 src1_sel:DWORD
	v_mov_b32_e32 v14, v13
	v_mov_b32_e32 v20, v12
	v_pk_add_f32 v[18:19], v[14:15], v[18:19]
	v_pk_add_f32 v[16:17], v[20:21], v[16:17]
	v_and_b32_e32 v13, 0xffff0000, v18
	v_and_b32_e32 v12, 0xffff0000, v16
	v_mul_f32_e32 v24, v13, v13
	v_fmac_f32_e32 v24, v12, v12
	v_and_b32_e32 v12, 0xffff0000, v17
	v_fmac_f32_e32 v24, v12, v12
	v_and_b32_e32 v14, 0xffff0000, v19
	v_fmac_f32_e32 v24, v14, v14
	v_or_b32_sdwa v12, v13, v16 dst_sel:DWORD dst_unused:UNUSED_PAD src0_sel:DWORD src1_sel:WORD_1
	v_or_b32_sdwa v13, v14, v17 dst_sel:DWORD dst_unused:UNUSED_PAD src0_sel:DWORD src1_sel:WORD_1
	v_lshlrev_b32_e32 v14, 16, v59
	v_lshlrev_b32_e32 v20, 16, v58
	v_or_b32_sdwa v15, v63, v14 dst_sel:DWORD dst_unused:UNUSED_PAD src0_sel:WORD_0 src1_sel:DWORD
	v_or_b32_sdwa v14, v62, v20 dst_sel:DWORD dst_unused:UNUSED_PAD src0_sel:WORD_0 src1_sel:DWORD
	v_and_b32_e32 v20, 0xffff0000, v59
	v_and_b32_e32 v22, 0xffff0000, v58
	v_or_b32_sdwa v21, v63, v20 dst_sel:DWORD dst_unused:UNUSED_PAD src0_sel:WORD_1 src1_sel:DWORD
	v_or_b32_sdwa v20, v62, v22 dst_sel:DWORD dst_unused:UNUSED_PAD src0_sel:WORD_1 src1_sel:DWORD
	v_mov_b32_e32 v22, v8
	v_mov_b32_e32 v23, v10
	v_pk_add_f32 v[22:23], v[22:23], v[14:15]
	v_mov_b32_e32 v10, v9
	v_pk_add_f32 v[8:9], v[10:11], v[20:21]
	v_and_b32_e32 v10, 0xffff0000, v22
	v_and_b32_e32 v11, 0xffff0000, v8
	v_and_b32_e32 v21, 0xffff0000, v9
	v_fmac_f32_e32 v24, v10, v10
	v_and_b32_e32 v16, 0xffff, v16
	v_and_b32_e32 v10, 0xffff, v22
	v_or_b32_sdwa v14, v11, v22 dst_sel:DWORD dst_unused:UNUSED_PAD src0_sel:DWORD src1_sel:WORD_1
	v_or_b32_sdwa v15, v21, v23 dst_sel:DWORD dst_unused:UNUSED_PAD src0_sel:DWORD src1_sel:WORD_1
	v_fmac_f32_e32 v24, v11, v11
	v_and_b32_e32 v17, 0xffff, v17
	v_and_b32_e32 v11, 0xffff, v23
	v_lshl_or_b32 v10, v8, 16, v10
	v_lshl_or_b32 v8, v18, 16, v16
	v_lshl_or_b32 v11, v9, 16, v11
	v_lshl_or_b32 v9, v19, 16, v17
	global_store_dwordx4 v[98:99], v[12:15], off
	global_store_dwordx4 v[100:101], v[8:11], off
	v_and_b32_e32 v20, 0xffff0000, v23
	v_and_b32_e32 v12, 0xffff0000, v52
	v_lshlrev_b32_e32 v8, 16, v53
	v_lshlrev_b32_e32 v10, 16, v52
	v_or_b32_sdwa v9, v49, v8 dst_sel:DWORD dst_unused:UNUSED_PAD src0_sel:WORD_0 src1_sel:DWORD
	v_or_b32_sdwa v8, v48, v10 dst_sel:DWORD dst_unused:UNUSED_PAD src0_sel:WORD_0 src1_sel:DWORD
	v_and_b32_e32 v10, 0xffff0000, v53
	v_or_b32_sdwa v11, v49, v10 dst_sel:DWORD dst_unused:UNUSED_PAD src0_sel:WORD_1 src1_sel:DWORD
	v_or_b32_sdwa v10, v48, v12 dst_sel:DWORD dst_unused:UNUSED_PAD src0_sel:WORD_1 src1_sel:DWORD
	v_mov_b32_e32 v12, v4
	v_mov_b32_e32 v13, v6
	v_fmac_f32_e32 v24, v20, v20
	v_pk_add_f32 v[8:9], v[12:13], v[8:9]
	v_mov_b32_e32 v6, v5
	v_fmac_f32_e32 v24, v21, v21
	v_pk_add_f32 v[12:13], v[6:7], v[10:11]
	v_and_b32_e32 v4, 0xffff0000, v8
	v_lshlrev_b32_e32 v6, 16, v55
	v_lshlrev_b32_e32 v10, 16, v54
	v_fmac_f32_e32 v24, v4, v4
	v_and_b32_e32 v4, 0xffff0000, v12
	v_or_b32_sdwa v7, v51, v6 dst_sel:DWORD dst_unused:UNUSED_PAD src0_sel:WORD_0 src1_sel:DWORD
	v_or_b32_sdwa v6, v50, v10 dst_sel:DWORD dst_unused:UNUSED_PAD src0_sel:WORD_0 src1_sel:DWORD
	v_and_b32_e32 v10, 0xffff0000, v55
	v_and_b32_e32 v14, 0xffff0000, v54
	v_fmac_f32_e32 v24, v4, v4
	v_and_b32_e32 v5, 0xffff0000, v9
	v_or_b32_sdwa v11, v51, v10 dst_sel:DWORD dst_unused:UNUSED_PAD src0_sel:WORD_1 src1_sel:DWORD
	v_or_b32_sdwa v10, v50, v14 dst_sel:DWORD dst_unused:UNUSED_PAD src0_sel:WORD_1 src1_sel:DWORD
	v_mov_b32_e32 v14, v0
	v_mov_b32_e32 v15, v2
	v_fmac_f32_e32 v24, v5, v5
	v_and_b32_e32 v5, 0xffff0000, v13
	v_pk_add_f32 v[14:15], v[14:15], v[6:7]
	v_mov_b32_e32 v2, v1
	v_fmac_f32_e32 v24, v5, v5
	v_pk_add_f32 v[0:1], v[2:3], v[10:11]
	v_and_b32_e32 v2, 0xffff0000, v14
	v_and_b32_e32 v3, 0xffff0000, v0
	v_fmac_f32_e32 v24, v2, v2
	v_and_b32_e32 v10, 0xffff0000, v15
	v_fmac_f32_e32 v24, v3, v3
	v_and_b32_e32 v11, 0xffff0000, v1
	v_fmac_f32_e32 v24, v10, v10
	v_fmac_f32_e32 v24, v11, v11
	v_or_b32_sdwa v4, v4, v8 dst_sel:DWORD dst_unused:UNUSED_PAD src0_sel:DWORD src1_sel:WORD_1
	v_and_b32_e32 v2, 0xffff, v8
	ds_bpermute_b32 v8, v207, v24
	v_or_b32_sdwa v5, v5, v9 dst_sel:DWORD dst_unused:UNUSED_PAD src0_sel:DWORD src1_sel:WORD_1
	v_or_b32_sdwa v6, v3, v14 dst_sel:DWORD dst_unused:UNUSED_PAD src0_sel:DWORD src1_sel:WORD_1
	v_and_b32_e32 v3, 0xffff, v9
	v_and_b32_e32 v9, 0xffff, v14
	v_and_b32_e32 v10, 0xffff, v15
	v_or_b32_sdwa v7, v11, v15 dst_sel:DWORD dst_unused:UNUSED_PAD src0_sel:DWORD src1_sel:WORD_1
	v_lshl_or_b32 v11, v1, 16, v10
	v_lshl_or_b32 v10, v0, 16, v9
	s_waitcnt lgkmcnt(0)
	v_add_f32_e32 v0, v24, v8
	ds_bpermute_b32 v1, v208, v0
	v_lshl_or_b32 v9, v13, 16, v3
	v_lshl_or_b32 v8, v12, 16, v2
	global_store_dwordx4 v[98:99], v[4:7], off offset:256
	global_store_dwordx4 v[100:101], v[8:11], off offset:256
	s_and_saveexec_b64 s[22:23], s[6:7]
	s_cbranch_execz .LBB0_795
	v_lshlrev_b64 v[2:3], 6, v[96:97]
	s_lshl_b32 s26, s50, 2
	v_lshl_add_u64 v[2:3], s[2:3], 0, v[2:3]
	s_ashr_i32 s27, s26, 31
	v_lshl_add_u64 v[2:3], s[26:27], 2, v[2:3]
	s_lshl_b32 s24, s46, 2
	v_lshl_add_u64 v[2:3], v[2:3], 0, s[24:25]
	s_waitcnt lgkmcnt(0)
	v_add_f32_e32 v0, v0, v1
	global_store_dword v[2:3], v0, off

.LBB0_1001:
	s_or_b64 exec, exec, s[34:35]
	v_or_b32_e32 v160, 48, v192
	v_ashrrev_i32_e32 v161, 31, v160
	s_waitcnt lgkmcnt(0)
	v_lshlrev_b64 v[112:113], 10, v[160:161]
	v_lshl_add_u64 v[166:167], v[112:113], 0, v[190:191]
	v_readlane_b32 s34, v247, 5
	v_lshlrev_b64 v[112:113], 1, v[166:167]
	v_readlane_b32 s35, v247, 6
	s_and_b64 vcc, exec, s[8:9]
	s_nop 0
	v_lshl_add_u64 v[162:163], s[34:35], 0, v[112:113]
	v_readlane_b32 s34, v249, 0
	v_readlane_b32 s35, v249, 1
	global_load_dwordx4 v[120:123], v[162:163], off offset:0
	s_nop 1
	v_lshl_add_u64 v[164:165], s[34:35], 0, v[112:113]
	global_load_dwordx4 v[124:127], v[164:165], off offset:0
	global_load_dwordx4 v[116:119], v[162:163], off offset:256
	global_load_dwordx4 v[112:115], v[164:165], off offset:256
	s_waitcnt vmcnt(12)
	s_nop 0
	v_lshlrev_b32_e32 v193, 16, v153
	v_lshlrev_b32_e32 v212, 16, v152
	v_and_b32_e32 v153, 0xffff0000, v153
	v_and_b32_e32 v152, 0xffff0000, v152
	v_or_b32_sdwa v213, v157, v193 dst_sel:DWORD dst_unused:UNUSED_PAD src0_sel:WORD_0 src1_sel:DWORD
	v_or_b32_sdwa v212, v156, v212 dst_sel:DWORD dst_unused:UNUSED_PAD src0_sel:WORD_0 src1_sel:DWORD
	v_or_b32_sdwa v157, v157, v153 dst_sel:DWORD dst_unused:UNUSED_PAD src0_sel:WORD_1 src1_sel:DWORD
	v_or_b32_sdwa v156, v156, v152 dst_sel:DWORD dst_unused:UNUSED_PAD src0_sel:WORD_1 src1_sel:DWORD
	v_mov_b32_e32 v153, v110
	v_mov_b32_e32 v110, v109
	v_mov_b32_e32 v152, v108
	v_pk_add_f32 v[110:111], v[110:111], v[156:157]
	v_lshlrev_b32_e32 v108, 16, v155
	v_lshlrev_b32_e32 v156, 16, v154
	v_and_b32_e32 v155, 0xffff0000, v155
	v_and_b32_e32 v154, 0xffff0000, v154
	v_or_b32_sdwa v109, v159, v108 dst_sel:DWORD dst_unused:UNUSED_PAD src0_sel:WORD_0 src1_sel:DWORD
	v_or_b32_sdwa v108, v158, v156 dst_sel:DWORD dst_unused:UNUSED_PAD src0_sel:WORD_0 src1_sel:DWORD
	v_or_b32_sdwa v155, v159, v155 dst_sel:DWORD dst_unused:UNUSED_PAD src0_sel:WORD_1 src1_sel:DWORD
	v_or_b32_sdwa v154, v158, v154 dst_sel:DWORD dst_unused:UNUSED_PAD src0_sel:WORD_1 src1_sel:DWORD
	v_mov_b32_e32 v156, v104
	v_mov_b32_e32 v157, v106
	v_mov_b32_e32 v106, v105
	v_pk_add_f32 v[152:153], v[152:153], v[212:213]
	v_pk_add_f32 v[108:109], v[156:157], v[108:109]
	v_pk_add_f32 v[106:107], v[106:107], v[154:155]
	v_lshl_add_u64 v[104:105], v[208:209], 2, s[2:3]
	s_cbranch_vccnz .LBB0_1003
	v_mov_b32_e32 v154, v152
	v_mov_b32_e32 v155, v110
	v_mov_b32_e32 v156, v153
	v_mov_b32_e32 v157, v111
	global_store_dwordx4 v[104:105], v[154:157], off
	s_mov_b64 s[34:35], 0
	s_nop 0
	v_mov_b32_e32 v154, v108
	v_mov_b32_e32 v155, v106
	v_mov_b32_e32 v156, v109
	v_mov_b32_e32 v157, v107
	global_store_dwordx4 v[104:105], v[154:157], off offset:16
	s_branch .LBB0_1004

.LBB0_1013:
	s_or_b64 exec, exec, s[34:35]
	v_add_u32_e32 v144, 0x80, v192
	v_ashrrev_i32_e32 v145, 31, v144
	s_waitcnt lgkmcnt(0)
	v_lshlrev_b64 v[96:97], 10, v[144:145]
	v_lshl_add_u64 v[150:151], v[96:97], 0, v[190:191]
	v_readlane_b32 s34, v247, 5
	v_lshlrev_b64 v[96:97], 1, v[150:151]
	v_readlane_b32 s35, v247, 6
	s_and_b64 vcc, exec, s[8:9]
	s_nop 0
	v_lshl_add_u64 v[146:147], s[34:35], 0, v[96:97]
	v_readlane_b32 s34, v249, 0
	v_readlane_b32 s35, v249, 1
	global_load_dwordx4 v[104:107], v[146:147], off offset:0
	s_nop 1
	v_lshl_add_u64 v[148:149], s[34:35], 0, v[96:97]
	global_load_dwordx4 v[108:111], v[148:149], off offset:0
	global_load_dwordx4 v[100:103], v[146:147], off offset:256
	global_load_dwordx4 v[96:99], v[148:149], off offset:256
	s_waitcnt vmcnt(16)
	s_nop 0
	v_lshlrev_b32_e32 v152, 16, v137
	v_lshlrev_b32_e32 v154, 16, v136
	v_and_b32_e32 v137, 0xffff0000, v137
	v_and_b32_e32 v136, 0xffff0000, v136
	v_or_b32_sdwa v153, v141, v152 dst_sel:DWORD dst_unused:UNUSED_PAD src0_sel:WORD_0 src1_sel:DWORD
	v_or_b32_sdwa v152, v140, v154 dst_sel:DWORD dst_unused:UNUSED_PAD src0_sel:WORD_0 src1_sel:DWORD
	v_or_b32_sdwa v141, v141, v137 dst_sel:DWORD dst_unused:UNUSED_PAD src0_sel:WORD_1 src1_sel:DWORD
	v_or_b32_sdwa v140, v140, v136 dst_sel:DWORD dst_unused:UNUSED_PAD src0_sel:WORD_1 src1_sel:DWORD
	v_mov_b32_e32 v137, v94
	v_mov_b32_e32 v94, v93
	v_mov_b32_e32 v136, v92
	v_pk_add_f32 v[94:95], v[94:95], v[140:141]
	v_lshlrev_b32_e32 v92, 16, v139
	v_lshlrev_b32_e32 v140, 16, v138
	v_and_b32_e32 v139, 0xffff0000, v139
	v_and_b32_e32 v138, 0xffff0000, v138
	v_or_b32_sdwa v93, v143, v92 dst_sel:DWORD dst_unused:UNUSED_PAD src0_sel:WORD_0 src1_sel:DWORD
	v_or_b32_sdwa v92, v142, v140 dst_sel:DWORD dst_unused:UNUSED_PAD src0_sel:WORD_0 src1_sel:DWORD
	v_or_b32_sdwa v139, v143, v139 dst_sel:DWORD dst_unused:UNUSED_PAD src0_sel:WORD_1 src1_sel:DWORD
	v_or_b32_sdwa v138, v142, v138 dst_sel:DWORD dst_unused:UNUSED_PAD src0_sel:WORD_1 src1_sel:DWORD
	v_mov_b32_e32 v140, v88
	v_mov_b32_e32 v141, v90
	v_mov_b32_e32 v90, v89
	v_pk_add_f32 v[136:137], v[136:137], v[152:153]
	v_pk_add_f32 v[92:93], v[140:141], v[92:93]
	v_pk_add_f32 v[90:91], v[90:91], v[138:139]
	v_lshl_add_u64 v[88:89], v[200:201], 2, s[2:3]
	s_cbranch_vccnz .LBB0_1015
	v_mov_b32_e32 v138, v136
	v_mov_b32_e32 v139, v94
	v_mov_b32_e32 v140, v137
	v_mov_b32_e32 v141, v95
	global_store_dwordx4 v[88:89], v[138:141], off
	s_mov_b64 s[34:35], 0
	s_nop 0
	v_mov_b32_e32 v138, v92
	v_mov_b32_e32 v139, v90
	v_mov_b32_e32 v140, v93
	v_mov_b32_e32 v141, v91
	global_store_dwordx4 v[88:89], v[138:141], off offset:16
	s_branch .LBB0_1016

.LBB0_1025:
	s_or_b64 exec, exec, s[34:35]
	v_add_u32_e32 v128, 0x90, v192
	v_ashrrev_i32_e32 v129, 31, v128
	s_waitcnt lgkmcnt(0)
	v_lshlrev_b64 v[80:81], 10, v[128:129]
	v_lshl_add_u64 v[134:135], v[80:81], 0, v[190:191]
	v_readlane_b32 s34, v247, 5
	v_lshlrev_b64 v[80:81], 1, v[134:135]
	v_readlane_b32 s35, v247, 6
	s_and_b64 vcc, exec, s[8:9]
	s_nop 0
	v_lshl_add_u64 v[130:131], s[34:35], 0, v[80:81]
	v_readlane_b32 s34, v249, 0
	v_readlane_b32 s35, v249, 1
	global_load_dwordx4 v[88:91], v[130:131], off offset:0
	s_nop 1
	v_lshl_add_u64 v[132:133], s[34:35], 0, v[80:81]
	global_load_dwordx4 v[92:95], v[132:133], off offset:0
	global_load_dwordx4 v[84:87], v[130:131], off offset:256
	global_load_dwordx4 v[80:83], v[132:133], off offset:256
	s_waitcnt vmcnt(16)
	s_nop 0
	v_lshlrev_b32_e32 v136, 16, v121
	v_lshlrev_b32_e32 v138, 16, v120
	v_and_b32_e32 v121, 0xffff0000, v121
	v_and_b32_e32 v120, 0xffff0000, v120
	v_or_b32_sdwa v137, v125, v136 dst_sel:DWORD dst_unused:UNUSED_PAD src0_sel:WORD_0 src1_sel:DWORD
	v_or_b32_sdwa v136, v124, v138 dst_sel:DWORD dst_unused:UNUSED_PAD src0_sel:WORD_0 src1_sel:DWORD
	v_or_b32_sdwa v125, v125, v121 dst_sel:DWORD dst_unused:UNUSED_PAD src0_sel:WORD_1 src1_sel:DWORD
	v_or_b32_sdwa v124, v124, v120 dst_sel:DWORD dst_unused:UNUSED_PAD src0_sel:WORD_1 src1_sel:DWORD
	v_mov_b32_e32 v121, v78
	v_mov_b32_e32 v78, v77
	v_mov_b32_e32 v120, v76
	v_pk_add_f32 v[78:79], v[78:79], v[124:125]
	v_lshlrev_b32_e32 v76, 16, v123
	v_lshlrev_b32_e32 v124, 16, v122
	v_and_b32_e32 v123, 0xffff0000, v123
	v_and_b32_e32 v122, 0xffff0000, v122
	v_or_b32_sdwa v77, v127, v76 dst_sel:DWORD dst_unused:UNUSED_PAD src0_sel:WORD_0 src1_sel:DWORD
	v_or_b32_sdwa v76, v126, v124 dst_sel:DWORD dst_unused:UNUSED_PAD src0_sel:WORD_0 src1_sel:DWORD
	v_or_b32_sdwa v123, v127, v123 dst_sel:DWORD dst_unused:UNUSED_PAD src0_sel:WORD_1 src1_sel:DWORD
	v_or_b32_sdwa v122, v126, v122 dst_sel:DWORD dst_unused:UNUSED_PAD src0_sel:WORD_1 src1_sel:DWORD
	v_mov_b32_e32 v124, v72
	v_mov_b32_e32 v125, v74
	v_mov_b32_e32 v74, v73
	v_pk_add_f32 v[120:121], v[120:121], v[136:137]
	v_pk_add_f32 v[76:77], v[124:125], v[76:77]
	v_pk_add_f32 v[74:75], v[74:75], v[122:123]
	v_lshl_add_u64 v[72:73], v[166:167], 2, s[2:3]
	s_cbranch_vccnz .LBB0_1027
	v_mov_b32_e32 v122, v120
	v_mov_b32_e32 v123, v78
	v_mov_b32_e32 v124, v121
	v_mov_b32_e32 v125, v79
	global_store_dwordx4 v[72:73], v[122:125], off
	s_mov_b64 s[34:35], 0
	s_nop 0
	v_mov_b32_e32 v122, v76
	v_mov_b32_e32 v123, v74
	v_mov_b32_e32 v124, v77
	v_mov_b32_e32 v125, v75
	global_store_dwordx4 v[72:73], v[122:125], off offset:16
	s_branch .LBB0_1028

.LBB0_1037:
	s_or_b64 exec, exec, s[34:35]
	v_add_u32_e32 v112, 0xa0, v192
	v_ashrrev_i32_e32 v113, 31, v112
	s_waitcnt lgkmcnt(0)
	v_lshlrev_b64 v[64:65], 10, v[112:113]
	v_lshl_add_u64 v[118:119], v[64:65], 0, v[190:191]
	v_readlane_b32 s34, v247, 5
	v_lshlrev_b64 v[64:65], 1, v[118:119]
	v_readlane_b32 s35, v247, 6
	s_and_b64 vcc, exec, s[8:9]
	s_nop 0
	v_lshl_add_u64 v[114:115], s[34:35], 0, v[64:65]
	v_readlane_b32 s34, v249, 0
	v_readlane_b32 s35, v249, 1
	global_load_dwordx4 v[72:75], v[114:115], off offset:0
	s_nop 1
	v_lshl_add_u64 v[116:117], s[34:35], 0, v[64:65]
	global_load_dwordx4 v[76:79], v[116:117], off offset:0
	global_load_dwordx4 v[68:71], v[114:115], off offset:256
	global_load_dwordx4 v[64:67], v[116:117], off offset:256
	s_waitcnt vmcnt(16)
	s_nop 0
	v_lshlrev_b32_e32 v120, 16, v105
	v_lshlrev_b32_e32 v122, 16, v104
	v_and_b32_e32 v105, 0xffff0000, v105
	v_and_b32_e32 v104, 0xffff0000, v104
	v_or_b32_sdwa v121, v109, v120 dst_sel:DWORD dst_unused:UNUSED_PAD src0_sel:WORD_0 src1_sel:DWORD
	v_or_b32_sdwa v120, v108, v122 dst_sel:DWORD dst_unused:UNUSED_PAD src0_sel:WORD_0 src1_sel:DWORD
	v_or_b32_sdwa v109, v109, v105 dst_sel:DWORD dst_unused:UNUSED_PAD src0_sel:WORD_1 src1_sel:DWORD
	v_or_b32_sdwa v108, v108, v104 dst_sel:DWORD dst_unused:UNUSED_PAD src0_sel:WORD_1 src1_sel:DWORD
	v_mov_b32_e32 v105, v62
	v_mov_b32_e32 v62, v61
	v_mov_b32_e32 v104, v60
	v_pk_add_f32 v[62:63], v[62:63], v[108:109]
	v_lshlrev_b32_e32 v60, 16, v107
	v_lshlrev_b32_e32 v108, 16, v106
	v_and_b32_e32 v107, 0xffff0000, v107
	v_and_b32_e32 v106, 0xffff0000, v106
	v_or_b32_sdwa v61, v111, v60 dst_sel:DWORD dst_unused:UNUSED_PAD src0_sel:WORD_0 src1_sel:DWORD
	v_or_b32_sdwa v60, v110, v108 dst_sel:DWORD dst_unused:UNUSED_PAD src0_sel:WORD_0 src1_sel:DWORD
	v_or_b32_sdwa v107, v111, v107 dst_sel:DWORD dst_unused:UNUSED_PAD src0_sel:WORD_1 src1_sel:DWORD
	v_or_b32_sdwa v106, v110, v106 dst_sel:DWORD dst_unused:UNUSED_PAD src0_sel:WORD_1 src1_sel:DWORD
	v_mov_b32_e32 v108, v56
	v_mov_b32_e32 v109, v58
	v_mov_b32_e32 v58, v57
	v_pk_add_f32 v[104:105], v[104:105], v[120:121]
	v_pk_add_f32 v[60:61], v[108:109], v[60:61]
	v_pk_add_f32 v[58:59], v[58:59], v[106:107]
	v_lshl_add_u64 v[56:57], v[150:151], 2, s[2:3]
	s_cbranch_vccnz .LBB0_1039
	v_mov_b32_e32 v106, v104
	v_mov_b32_e32 v107, v62
	v_mov_b32_e32 v108, v105
	v_mov_b32_e32 v109, v63
	global_store_dwordx4 v[56:57], v[106:109], off
	s_mov_b64 s[34:35], 0
	s_nop 0
	v_mov_b32_e32 v106, v60
	v_mov_b32_e32 v107, v58
	v_mov_b32_e32 v108, v61
	v_mov_b32_e32 v109, v59
	global_store_dwordx4 v[56:57], v[106:109], off offset:16
	s_branch .LBB0_1040

.LBB0_1049:
	s_or_b64 exec, exec, s[34:35]
	v_add_u32_e32 v96, 0xb0, v192
	v_ashrrev_i32_e32 v97, 31, v96
	s_waitcnt lgkmcnt(0)
	v_lshlrev_b64 v[48:49], 10, v[96:97]
	v_lshl_add_u64 v[102:103], v[48:49], 0, v[190:191]
	v_readlane_b32 s34, v247, 5
	v_lshlrev_b64 v[48:49], 1, v[102:103]
	v_readlane_b32 s35, v247, 6
	s_and_b64 vcc, exec, s[8:9]
	s_nop 0
	v_lshl_add_u64 v[98:99], s[34:35], 0, v[48:49]
	v_readlane_b32 s34, v249, 0
	v_readlane_b32 s35, v249, 1
	global_load_dwordx4 v[56:59], v[98:99], off offset:0
	s_nop 1
	v_lshl_add_u64 v[100:101], s[34:35], 0, v[48:49]
	global_load_dwordx4 v[60:63], v[100:101], off offset:0
	global_load_dwordx4 v[52:55], v[98:99], off offset:256
	global_load_dwordx4 v[48:51], v[100:101], off offset:256
	s_waitcnt vmcnt(16)
	s_nop 0
	v_lshlrev_b32_e32 v104, 16, v89
	v_lshlrev_b32_e32 v106, 16, v88
	v_and_b32_e32 v89, 0xffff0000, v89
	v_and_b32_e32 v88, 0xffff0000, v88
	v_or_b32_sdwa v105, v93, v104 dst_sel:DWORD dst_unused:UNUSED_PAD src0_sel:WORD_0 src1_sel:DWORD
	v_or_b32_sdwa v104, v92, v106 dst_sel:DWORD dst_unused:UNUSED_PAD src0_sel:WORD_0 src1_sel:DWORD
	v_or_b32_sdwa v93, v93, v89 dst_sel:DWORD dst_unused:UNUSED_PAD src0_sel:WORD_1 src1_sel:DWORD
	v_or_b32_sdwa v92, v92, v88 dst_sel:DWORD dst_unused:UNUSED_PAD src0_sel:WORD_1 src1_sel:DWORD
	v_mov_b32_e32 v89, v46
	v_mov_b32_e32 v46, v45
	v_mov_b32_e32 v88, v44
	v_pk_add_f32 v[46:47], v[46:47], v[92:93]
	v_lshlrev_b32_e32 v44, 16, v91
	v_lshlrev_b32_e32 v92, 16, v90
	v_and_b32_e32 v91, 0xffff0000, v91
	v_and_b32_e32 v90, 0xffff0000, v90
	v_or_b32_sdwa v45, v95, v44 dst_sel:DWORD dst_unused:UNUSED_PAD src0_sel:WORD_0 src1_sel:DWORD
	v_or_b32_sdwa v44, v94, v92 dst_sel:DWORD dst_unused:UNUSED_PAD src0_sel:WORD_0 src1_sel:DWORD
	v_or_b32_sdwa v91, v95, v91 dst_sel:DWORD dst_unused:UNUSED_PAD src0_sel:WORD_1 src1_sel:DWORD
	v_or_b32_sdwa v90, v94, v90 dst_sel:DWORD dst_unused:UNUSED_PAD src0_sel:WORD_1 src1_sel:DWORD
	v_mov_b32_e32 v92, v40
	v_mov_b32_e32 v93, v42
	v_mov_b32_e32 v42, v41
	v_pk_add_f32 v[88:89], v[88:89], v[104:105]
	v_pk_add_f32 v[44:45], v[92:93], v[44:45]
	v_pk_add_f32 v[42:43], v[42:43], v[90:91]
	v_lshl_add_u64 v[40:41], v[134:135], 2, s[2:3]
	s_cbranch_vccnz .LBB0_1051
	v_mov_b32_e32 v90, v88
	v_mov_b32_e32 v91, v46
	v_mov_b32_e32 v92, v89
	v_mov_b32_e32 v93, v47
	global_store_dwordx4 v[40:41], v[90:93], off
	s_mov_b64 s[34:35], 0
	s_nop 0
	v_mov_b32_e32 v90, v44
	v_mov_b32_e32 v91, v42
	v_mov_b32_e32 v92, v45
	v_mov_b32_e32 v93, v43
	global_store_dwordx4 v[40:41], v[90:93], off offset:16
	s_branch .LBB0_1052

.LBB0_1061:
	s_or_b64 exec, exec, s[34:35]
	s_waitcnt vmcnt(12)
	v_mov_b32_e32 v37, v30
	v_lshlrev_b32_e32 v32, 16, v73
	v_lshlrev_b32_e32 v34, 16, v72
	v_and_b32_e32 v35, 0xffff0000, v73
	s_waitcnt lgkmcnt(0)
	v_or_b32_sdwa v33, v77, v32 dst_sel:DWORD dst_unused:UNUSED_PAD src0_sel:WORD_0 src1_sel:DWORD
	v_or_b32_sdwa v32, v76, v34 dst_sel:DWORD dst_unused:UNUSED_PAD src0_sel:WORD_0 src1_sel:DWORD
	v_and_b32_e32 v34, 0xffff0000, v72
	v_or_b32_sdwa v35, v77, v35 dst_sel:DWORD dst_unused:UNUSED_PAD src0_sel:WORD_1 src1_sel:DWORD
	v_or_b32_sdwa v34, v76, v34 dst_sel:DWORD dst_unused:UNUSED_PAD src0_sel:WORD_1 src1_sel:DWORD
	v_mov_b32_e32 v30, v29
	v_mov_b32_e32 v36, v28
	v_pk_add_f32 v[30:31], v[30:31], v[34:35]
	v_lshlrev_b32_e32 v28, 16, v75
	v_lshlrev_b32_e32 v34, 16, v74
	v_pk_add_f32 v[32:33], v[36:37], v[32:33]
	v_or_b32_sdwa v29, v79, v28 dst_sel:DWORD dst_unused:UNUSED_PAD src0_sel:WORD_0 src1_sel:DWORD
	v_or_b32_sdwa v28, v78, v34 dst_sel:DWORD dst_unused:UNUSED_PAD src0_sel:WORD_0 src1_sel:DWORD
	v_and_b32_e32 v34, 0xffff0000, v75
	v_and_b32_e32 v36, 0xffff0000, v74
	v_or_b32_sdwa v35, v79, v34 dst_sel:DWORD dst_unused:UNUSED_PAD src0_sel:WORD_1 src1_sel:DWORD
	v_or_b32_sdwa v34, v78, v36 dst_sel:DWORD dst_unused:UNUSED_PAD src0_sel:WORD_1 src1_sel:DWORD
	v_mov_b32_e32 v36, v24
	v_mov_b32_e32 v37, v26
	v_mov_b32_e32 v26, v25
	v_pk_add_f32 v[28:29], v[36:37], v[28:29]
	v_pk_add_f32 v[26:27], v[26:27], v[34:35]
	s_and_b64 vcc, exec, s[8:9]
	v_lshl_add_u64 v[24:25], v[118:119], 2, s[2:3]
	s_cbranch_vccnz .LBB0_1063
	v_mov_b32_e32 v34, v32
	v_mov_b32_e32 v35, v30
	v_mov_b32_e32 v36, v33
	v_mov_b32_e32 v37, v31
	global_store_dwordx4 v[24:25], v[34:37], off
	s_mov_b64 s[34:35], 0
	s_nop 0
	v_mov_b32_e32 v34, v28
	v_mov_b32_e32 v35, v26
	v_mov_b32_e32 v36, v29
	v_mov_b32_e32 v37, v27
	global_store_dwordx4 v[24:25], v[34:37], off offset:16
	s_branch .LBB0_1064

.LBB0_1073:
	s_or_b64 exec, exec, s[34:35]
	s_waitcnt vmcnt(8)
	v_mov_b32_e32 v21, v14
	v_lshlrev_b32_e32 v16, 16, v57
	v_lshlrev_b32_e32 v18, 16, v56
	v_and_b32_e32 v19, 0xffff0000, v57
	s_waitcnt lgkmcnt(0)
	v_or_b32_sdwa v17, v61, v16 dst_sel:DWORD dst_unused:UNUSED_PAD src0_sel:WORD_0 src1_sel:DWORD
	v_or_b32_sdwa v16, v60, v18 dst_sel:DWORD dst_unused:UNUSED_PAD src0_sel:WORD_0 src1_sel:DWORD
	v_and_b32_e32 v18, 0xffff0000, v56
	v_or_b32_sdwa v19, v61, v19 dst_sel:DWORD dst_unused:UNUSED_PAD src0_sel:WORD_1 src1_sel:DWORD
	v_or_b32_sdwa v18, v60, v18 dst_sel:DWORD dst_unused:UNUSED_PAD src0_sel:WORD_1 src1_sel:DWORD
	v_mov_b32_e32 v14, v13
	v_mov_b32_e32 v20, v12
	v_pk_add_f32 v[14:15], v[14:15], v[18:19]
	v_lshlrev_b32_e32 v12, 16, v59
	v_lshlrev_b32_e32 v18, 16, v58
	v_pk_add_f32 v[16:17], v[20:21], v[16:17]
	v_or_b32_sdwa v13, v63, v12 dst_sel:DWORD dst_unused:UNUSED_PAD src0_sel:WORD_0 src1_sel:DWORD
	v_or_b32_sdwa v12, v62, v18 dst_sel:DWORD dst_unused:UNUSED_PAD src0_sel:WORD_0 src1_sel:DWORD
	v_and_b32_e32 v18, 0xffff0000, v59
	v_and_b32_e32 v20, 0xffff0000, v58
	v_or_b32_sdwa v19, v63, v18 dst_sel:DWORD dst_unused:UNUSED_PAD src0_sel:WORD_1 src1_sel:DWORD
	v_or_b32_sdwa v18, v62, v20 dst_sel:DWORD dst_unused:UNUSED_PAD src0_sel:WORD_1 src1_sel:DWORD
	v_mov_b32_e32 v20, v8
	v_mov_b32_e32 v21, v10
	v_mov_b32_e32 v10, v9
	v_pk_add_f32 v[12:13], v[20:21], v[12:13]
	v_pk_add_f32 v[10:11], v[10:11], v[18:19]
	s_and_b64 vcc, exec, s[8:9]
	v_lshl_add_u64 v[8:9], v[102:103], 2, s[2:3]
	s_cbranch_vccnz .LBB0_1075
	v_mov_b32_e32 v18, v16
	v_mov_b32_e32 v19, v14
	v_mov_b32_e32 v20, v17
	v_mov_b32_e32 v21, v15
	global_store_dwordx4 v[8:9], v[18:21], off
	s_mov_b64 s[34:35], 0
	s_nop 0
	v_mov_b32_e32 v18, v12
	v_mov_b32_e32 v19, v10
	v_mov_b32_e32 v20, v13
	v_mov_b32_e32 v21, v11
	global_store_dwordx4 v[8:9], v[18:21], off offset:16
	s_branch .LBB0_1076
